# NSA tile loops: the 100 v_pk_fma_f32 that build the ALiBi accumulator init between QK MFMAs are issued as two v_fma_f32 each (same arithmetic)
# speedup vs baseline: 1.0012x; 1.0012x over previous
; #define LAS __attribute__((address_space(3)))
; __device__ __forceinline__ void nsa_phase(LAS unsigned char* lds, const Args& a, const bf16_t* z, const bf16_t* KC, const bf16_t* VCT, const bf16_t* VST, const bf16_t* VWT, bf16_t* A2, int ldo, bool merged) {
;     ...
;         __syncthreads();
;         if (!kc_resident) {
; #pragma unroll
;             for (int it = 0; it < 4; ++it) {
;                 const int row = it * 64 + (tid >> 3), ch = tid & 7;
;                 *(LAS u32x4*)(lds + NS_KCL + row * 144 + ch * 16) = *(const u32x4*)(KC + ((size_t)bg * 256 + row) * 256 + ch * 8);
;                 const int dim = tid >> 3, c16 = (tid & 7) + 8 * it;
;                 *(LAS u32x4*)(lds + NS_VCL + dim * 528 + c16 * 16) = *(const u32x4*)(VCT + ((size_t)bg * 64 + dim) * 256 + c16 * 8);
;             }
;         }
;         if (tid == 0) { UNI[0] = 0u; UNI[1] = 0u; }
;         bf16x8 Qf[2][2]; int tq[2]; float gate[2][3];
; #pragma unroll
;         for (int qs = 0; qs < 2; ++qs) {
;             const int ql = qh * 32 + qs * 16 + l15; tq[qs] = t0 + ql;
;             const bf16_t* zr = z + (row0 + ql) * ZLD;
;             Qf[qs][0] = *(const bf16x8*)(zr + ZQ + hq * 64 + g4 * 8);
;             Qf[qs][1] = *(const bf16x8*)(zr + ZQ + hq * 64 + 32 + g4 * 8);
; #pragma unroll
;             for (int br = 0; br < 3; ++br) gate[qs][br] = sigm(bf2f(zr[ZGT + hq * 3 + br]) + gbias[hq * 3 + br]);
;         }
;         f32x4 Y[4][2];
; #pragma unroll
;         for (int d = 0; d < 4; ++d) { Y[d][0] = (f32x4){0.f, 0.f, 0.f, 0.f}; Y[d][1] = Y[d][0]; }
;         __syncthreads();
;     ...
;             for (int tl = 0; tl < 4; ++tl) {
;                 if (tl <= tlmax) {
; #pragma unroll
;                     for (int s = 0; s < 4; ++s) {
;                         const LAS unsigned char* kp = lds + kcl_off + (tl * 64 + s * 16) * 144;
;                         const bf16x8 k0 = *(const LAS bf16x8*)kp, k1 = *(const LAS bf16x8*)(kp + 64);
;                         const float cb = slope * (float)((tl * 1024 + s * 256 + 64 * g4 + 31) - tq[qs]);
;                         f32x4 zz;
; #pragma unroll
;                         for (int i = 0; i < 4; ++i) zz[i] = fmaf(slope, 16.f * (float)i, cb);
;                         zz = MFMA16(k0, Qf[qs][0], zz);
;                         zz = MFMA16(k1, Qf[qs][1], zz);
;                         if (!((64 * (tl + 1) - 1) <= (4 * qt - 2))) {
; #pragma unroll
.LBB0_913:
	v_mov_b32_e32 v170, v157
	v_mov_b32_e32 v136, v159
	s_movk_i32 s0, 0x210
	v_mul_lo_u32 v134, v170, s83
	v_lshl_add_u32 v135, v136, 4, v134
	v_lshlrev_b32_e32 v112, 3, v136
	v_mul_lo_u32 v1, v170, s0
	s_mov_b32 s0, 0x9000
	v_mov_b32_e32 v130, v156
	v_add3_u32 v119, v1, v112, s0
	v_mov_b32_e32 v1, v135
	s_waitcnt lgkmcnt(0)
	s_barrier
	s_mov_b64 s[0:1], exec
	v_readlane_b32 s6, v247, 1
	v_readlane_b32 s7, v247, 2
	s_and_b64 s[6:7], s[0:1], s[6:7]
	s_mov_b64 exec, s[6:7]
	v_mov_b32_e32 v2, s82
	ds_write_b64 v2, v[168:169]
	s_or_b64 exec, exec, s[0:1]
	s_lshl_b32 s0, s62, 8
	s_cmp_lt_u32 s62, 8
	s_cselect_b32 s0, s0, 0x680
	s_add_i32 s0, s0, s2
	s_and_b32 s1, s0, 0x100
	s_bfe_u32 s0, s0, 0x60005
	s_xor_b32 s6, s0, 7
	s_cmp_eq_u32 s1, 0
	s_cselect_b32 s63, s0, s6
	s_lshl_b32 s22, s63, 6
	v_add_u32_e32 v2, s95, v170
	s_or_b32 s68, s22, s34
	s_mov_b32 s69, s61
	v_ashrrev_i32_e32 v3, 31, v2
	v_lshl_add_u64 v[4:5], s[68:69], 0, v[2:3]
	v_mad_u64_u32 v[12:13], s[0:1], v4, s3, v[166:167]
	v_ashrrev_i32_e32 v113, 31, v112
	v_mad_i32_i24 v13, v5, s3, v13
	s_mov_b32 s77, s61
	v_lshl_add_u64 v[4:5], v[12:13], 0, s[76:77]
	v_lshlrev_b64 v[14:15], 1, v[112:113]
	v_lshl_add_u64 v[8:9], v[4:5], 0, v[14:15]
	v_add_u32_e32 v96, 16, v2
	global_load_dwordx4 v[4:7], v[8:9], off
	s_nop 0
	global_load_dwordx4 v[8:11], v[8:9], off offset:64
	v_readlane_b32 s0, v246, 16
	v_ashrrev_i32_e32 v97, 31, v96
	v_readlane_b32 s1, v246, 17
	v_lshl_add_u64 v[16:17], s[68:69], 0, v[96:97]
	s_mov_b32 s79, s61
	v_lshl_add_u64 v[12:13], v[12:13], 0, s[78:79]
	v_add_u32_e32 v97, 0, v1
	v_lshlrev_b32_e32 v116, 6, v136
	global_load_dwordx3 v[52:54], v0, s[0:1]
	v_mad_u64_u32 v[18:19], s[0:1], v16, s3, v[166:167]
	v_mad_i32_i24 v19, v17, s3, v19
	v_lshl_add_u64 v[16:17], v[18:19], 0, s[76:77]
	v_lshl_add_u64 v[16:17], v[16:17], 0, v[14:15]
	global_load_dword v58, v[12:13], off
	global_load_ushort v57, v[12:13], off offset:4
	s_nop 0
	global_load_dwordx4 v[12:15], v[16:17], off
	v_lshl_add_u64 v[20:21], v[18:19], 0, s[78:79]
	global_load_dwordx4 v[16:19], v[16:17], off offset:64
	s_nop 0
	global_load_dword v56, v[20:21], off
	global_load_ushort v55, v[20:21], off offset:4
	s_waitcnt lgkmcnt(0)
	s_barrier
	ds_read_b128 v[20:23], v97
	ds_read_b128 v[24:27], v97 offset:64
	v_add_u32_e32 v138, s22, v2
	v_or_b32_e32 v117, 31, v116
	v_sub_u32_e32 v2, v117, v138
	v_cvt_f32_i32_e32 v1, v2
	s_cmp_lt_u32 s63, 17
	s_cselect_b64 s[0:1], -1, 0
	s_cmp_gt_u32 s63, 16
	v_mul_f32_e32 v28, v160, v1
	v_fma_f32 v30, v162, s90, v28
	v_fma_f32 v31, v163, s91, v28
	v_fma_f32 v29, v165, s59, v28
	v_fma_f32 v28, v164, s58, v28
	v_sub_u32_e32 v1, v138, v116
	s_waitcnt vmcnt(8) lgkmcnt(1)
	v_mfma_f32_16x16x32_bf16 v[20:23], v[20:23], v[4:7], v[28:31]
	s_waitcnt vmcnt(7) lgkmcnt(0)
	v_mfma_f32_16x16x32_bf16 v[20:23], v[24:27], v[8:11], v[20:23]
	s_cbranch_scc1 .LBB0_917
	v_subrev_u32_e32 v3, 31, v1
	v_cmp_lt_i32_e32 vcc, -1, v3
	v_subrev_u32_e32 v3, 47, v1
	s_nop 3
	v_cndmask_b32_e32 v20, v194, v20, vcc
	v_cmp_lt_i32_e32 vcc, -1, v3
	v_subrev_u32_e32 v3, 63, v1
	s_nop 0
	v_cndmask_b32_e32 v21, v194, v21, vcc
	v_cmp_lt_i32_e32 vcc, -1, v3
	v_add_u32_e32 v3, 0xffffffb1, v1
	s_nop 0
	v_cndmask_b32_e32 v22, v194, v22, vcc
	v_cmp_lt_i32_e32 vcc, -1, v3
	s_nop 1
	v_cndmask_b32_e32 v23, v194, v23, vcc
.LBB0_917:
	ds_read_b128 v[24:27], v97 offset:2304
	ds_read_b128 v[28:31], v97 offset:2368
	v_add_u32_e32 v3, 0x100, v2
	v_cvt_f32_i32_e32 v3, v3
	v_mov_b32_e32 v161, v160
	s_andn2_b64 vcc, exec, s[0:1]
	v_mul_f32_e32 v32, v160, v3
	v_fma_f32 v34, v160, s90, v32
	v_fma_f32 v35, v161, s91, v32
	v_fma_f32 v33, v165, s59, v32
	v_fma_f32 v32, v164, s58, v32
	v_cndmask_b32_e64 v3, 0, 1, s[0:1]
	v_cmp_ne_u32_e64 s[16:17], 1, v3
	s_waitcnt lgkmcnt(1)
	v_mfma_f32_16x16x32_bf16 v[24:27], v[24:27], v[4:7], v[32:35]
	s_waitcnt lgkmcnt(0)
	v_mfma_f32_16x16x32_bf16 v[24:27], v[28:31], v[8:11], v[24:27]
	s_cbranch_vccnz .LBB0_919
	v_add_u32_e32 v3, 0xfffffee1, v1
	v_cmp_lt_i32_e32 vcc, -1, v3
	v_add_u32_e32 v3, 0xfffffed1, v1
	s_nop 3
	v_cndmask_b32_e32 v24, v194, v24, vcc
	v_cmp_lt_i32_e32 vcc, -1, v3
	v_add_u32_e32 v3, 0xfffffec1, v1
	s_nop 0
	v_cndmask_b32_e32 v25, v194, v25, vcc
	v_cmp_lt_i32_e32 vcc, -1, v3
	v_add_u32_e32 v3, 0xfffffeb1, v1
	s_nop 0
	v_cndmask_b32_e32 v26, v194, v26, vcc
	v_cmp_lt_i32_e32 vcc, -1, v3
	s_nop 1
	v_cndmask_b32_e32 v27, v194, v27, vcc
.LBB0_919:
	ds_read_b128 v[28:31], v97 offset:4608
	v_add_u32_e32 v3, 0x200, v2
	v_cvt_f32_i32_e32 v3, v3
	s_and_b64 vcc, exec, s[16:17]
	v_mul_f32_e32 v32, v160, v3
	v_fma_f32 v34, v160, s90, v32
	v_fma_f32 v35, v161, s91, v32
	v_fma_f32 v33, v165, s59, v32
	v_fma_f32 v32, v164, s58, v32
	s_waitcnt lgkmcnt(0)
	s_nop 0
	v_mfma_f32_16x16x32_bf16 v[28:31], v[28:31], v[4:7], v[32:35]
	s_nop 2
	ds_read_b128 v[32:35], v97 offset:4672
	s_waitcnt lgkmcnt(0)
	v_mfma_f32_16x16x32_bf16 v[28:31], v[32:35], v[8:11], v[28:31]
	s_cbranch_vccnz .LBB0_921
	v_add_u32_e32 v3, 0xfffffde1, v1
	v_cmp_lt_i32_e32 vcc, -1, v3
	v_add_u32_e32 v3, 0xfffffdd1, v1
	s_nop 3
	v_cndmask_b32_e32 v28, v194, v28, vcc
	v_cmp_lt_i32_e32 vcc, -1, v3
	v_add_u32_e32 v3, 0xfffffdc1, v1
	s_nop 0
	v_cndmask_b32_e32 v29, v194, v29, vcc
	v_cmp_lt_i32_e32 vcc, -1, v3
	v_add_u32_e32 v3, 0xfffffdb1, v1
	s_nop 0
	v_cndmask_b32_e32 v30, v194, v30, vcc
	v_cmp_lt_i32_e32 vcc, -1, v3
	s_nop 1
	v_cndmask_b32_e32 v31, v194, v31, vcc
; #define LAS __attribute__((address_space(3)))
; #define MFMA16(a, b, c) __builtin_amdgcn_mfma_f32_16x16x32_bf16(a, b, c, 0, 0, 0)
; __device__ __forceinline__ void nsa_phase(LAS unsigned char* lds, const Args& a, const bf16_t* z, const bf16_t* KC, const bf16_t* VCT, const bf16_t* VST, const bf16_t* VWT, bf16_t* A2, int ldo, bool merged) {
;     ...
;             for (int tl = 0; tl < 4; ++tl) {
;                 if (tl <= tlmax) {
; #pragma unroll
;                     for (int s = 0; s < 4; ++s) {
;                         const LAS unsigned char* kp = lds + kcl_off + (tl * 64 + s * 16) * 144;
;                         const bf16x8 k0 = *(const LAS bf16x8*)kp, k1 = *(const LAS bf16x8*)(kp + 64);
;                         const float cb = slope * (float)((tl * 1024 + s * 256 + 64 * g4 + 31) - tq[qs]);
;                         f32x4 zz;
; #pragma unroll
;                         for (int i = 0; i < 4; ++i) zz[i] = fmaf(slope, 16.f * (float)i, cb);
;                         zz = MFMA16(k0, Qf[qs][0], zz);
;                         zz = MFMA16(k1, Qf[qs][1], zz);
;                         if (!((64 * (tl + 1) - 1) <= (4 * qt - 2))) {
; #pragma unroll
;                             for (int i = 0; i < 4; ++i) {
;                                 const int dist = (tq[qs] - 31 - 64 * g4) - (tl * 1024 + s * 256 + 16 * i);
;                                 const bool ok = (dist >= 0) && !(tl == 3 && s == 3 && i == 3 && g4 == 3);
;                                 zz[i] = ok ? zz[i] : -1e30f;
;                             }
;                         }
; #pragma unroll
;                         for (int i = 0; i < 4; ++i) mx = fmaxf(mx, zz[i]);
;                         sc[tl][s] = zz;
;                         __builtin_amdgcn_sched_barrier(0);
;                     }
;                 } else {
; #pragma unroll
;                     for (int s = 0; s < 4; ++s) sc[tl][s] = (f32x4){-1e30f, -1e30f, -1e30f, -1e30f};
;                 }
;             }
;             mx = fmaxf(mx, __shfl_xor(mx, 16)); mx = fmaxf(mx, __shfl_xor(mx, 32));
.LBB0_921:
	ds_read_b128 v[32:35], v97 offset:6912
	v_add_u32_e32 v3, 0x300, v2
	v_cvt_f32_i32_e32 v3, v3
	v_mov_b32_e32 v161, v160
	s_and_b64 vcc, exec, s[16:17]
	v_mul_f32_e32 v36, v160, v3
	v_fma_f32 v38, v160, s90, v36
	v_fma_f32 v39, v161, s91, v36
	v_fma_f32 v37, v165, s59, v36
	v_fma_f32 v36, v164, s58, v36
	s_waitcnt lgkmcnt(0)
	s_nop 0
	v_mfma_f32_16x16x32_bf16 v[32:35], v[32:35], v[4:7], v[36:39]
	s_nop 2
	ds_read_b128 v[36:39], v97 offset:6976
	s_waitcnt lgkmcnt(0)
	v_mfma_f32_16x16x32_bf16 v[32:35], v[36:39], v[8:11], v[32:35]
	s_cbranch_vccnz .LBB0_923
	v_add_u32_e32 v3, 0xfffffce1, v1
	v_cmp_lt_i32_e32 vcc, -1, v3
	v_add_u32_e32 v3, 0xfffffcd1, v1
	s_nop 3
	v_cndmask_b32_e32 v32, v194, v32, vcc
	v_cmp_lt_i32_e32 vcc, -1, v3
	v_add_u32_e32 v3, 0xfffffcc1, v1
	s_nop 0
	v_cndmask_b32_e32 v33, v194, v33, vcc
	v_cmp_lt_i32_e32 vcc, -1, v3
	v_add_u32_e32 v3, 0xfffffcb1, v1
	s_nop 0
	v_cndmask_b32_e32 v34, v194, v34, vcc
	v_cmp_lt_i32_e32 vcc, -1, v3
	s_nop 1
	v_cndmask_b32_e32 v35, v194, v35, vcc
.LBB0_923:
	v_mov_b32_e32 v39, 0xf149f2ca
	v_max3_f32 v3, v20, v39, v21
	v_max3_f32 v3, v3, v22, v23
	v_max3_f32 v3, v3, v24, v25
	v_max3_f32 v3, v3, v26, v27
	v_max3_f32 v3, v3, v28, v29
	v_max3_f32 v3, v3, v30, v31
	v_max3_f32 v3, v3, v32, v33
	v_max3_f32 v3, v3, v34, v35
	s_cmp_gt_u32 s63, 15
	s_cselect_b64 s[6:7], -1, 0
	s_cmp_lt_u32 s63, 16
	s_cbranch_scc1 .LBB0_933
	ds_read_b128 v[36:39], v97 offset:9216
	v_add_u32_e32 v40, 0x400, v2
	v_cvt_f32_i32_e32 v44, v40
	ds_read_b128 v[40:43], v97 offset:9280
	v_mov_b32_e32 v161, v160
	s_cmp_lt_u32 s63, 33
	v_mul_f32_e32 v44, v160, v44
	v_fma_f32 v46, v160, s90, v44
	v_fma_f32 v47, v161, s91, v44
	v_fma_f32 v45, v165, s59, v44
	v_fma_f32 v44, v164, s58, v44
	s_cselect_b64 s[8:9], -1, 0
	s_cmp_gt_u32 s63, 32
	s_waitcnt lgkmcnt(1)
	v_mfma_f32_16x16x32_bf16 v[36:39], v[36:39], v[4:7], v[44:47]
	s_waitcnt lgkmcnt(0)
	v_mfma_f32_16x16x32_bf16 v[36:39], v[40:43], v[8:11], v[36:39]
	s_cbranch_scc1 .LBB0_926
	v_add_u32_e32 v40, 0xfffffbe1, v1
	v_cmp_lt_i32_e32 vcc, -1, v40
	v_add_u32_e32 v40, 0xfffffbd1, v1
	s_nop 3
	v_cndmask_b32_e32 v36, v194, v36, vcc
	v_cmp_lt_i32_e32 vcc, -1, v40
	v_add_u32_e32 v40, 0xfffffbc1, v1
	s_nop 0
	v_cndmask_b32_e32 v37, v194, v37, vcc
	v_cmp_lt_i32_e32 vcc, -1, v40
	v_add_u32_e32 v40, 0xfffffbb1, v1
	s_nop 0
	v_cndmask_b32_e32 v38, v194, v38, vcc
	v_cmp_lt_i32_e32 vcc, -1, v40
	s_nop 1
	v_cndmask_b32_e32 v39, v194, v39, vcc
.LBB0_926:
	ds_read_b128 v[40:43], v97 offset:11520
	v_add_u32_e32 v44, 0x500, v2
	v_cvt_f32_i32_e32 v48, v44
	ds_read_b128 v[44:47], v97 offset:11584
	s_andn2_b64 vcc, exec, s[8:9]
	v_mul_f32_e32 v48, v160, v48
	v_fma_f32 v50, v160, s90, v48
	v_fma_f32 v51, v161, s91, v48
	v_fma_f32 v49, v165, s59, v48
	v_fma_f32 v48, v164, s58, v48
	s_waitcnt lgkmcnt(1)
	s_nop 0
	v_mfma_f32_16x16x32_bf16 v[40:43], v[40:43], v[4:7], v[48:51]
	s_waitcnt lgkmcnt(0)
	v_mfma_f32_16x16x32_bf16 v[40:43], v[44:47], v[8:11], v[40:43]
	s_nop 0
	v_cndmask_b32_e64 v48, 0, 1, s[8:9]
	v_cmp_ne_u32_e64 s[0:1], 1, v48
	s_cbranch_vccnz .LBB0_928
	v_add_u32_e32 v44, 0xfffffae1, v1
	v_cmp_lt_i32_e32 vcc, -1, v44
	v_add_u32_e32 v44, 0xfffffad1, v1
	s_nop 0
	v_cndmask_b32_e32 v40, v194, v40, vcc
	v_cmp_lt_i32_e32 vcc, -1, v44
	v_add_u32_e32 v44, 0xfffffac1, v1
	s_nop 0
	v_cndmask_b32_e32 v41, v194, v41, vcc
	v_cmp_lt_i32_e32 vcc, -1, v44
	v_add_u32_e32 v44, 0xfffffab1, v1
	s_nop 0
	v_cndmask_b32_e32 v42, v194, v42, vcc
	v_cmp_lt_i32_e32 vcc, -1, v44
	s_nop 1
	v_cndmask_b32_e32 v43, v194, v43, vcc
.LBB0_928:
	ds_read_b128 v[44:47], v97 offset:13824
	v_add_u32_e32 v48, 0x600, v2
	v_cvt_f32_i32_e32 v48, v48
	v_mov_b32_e32 v161, v160
	s_and_b64 vcc, exec, s[0:1]
	v_mul_f32_e32 v48, v160, v48
	v_fma_f32 v50, v160, s90, v48
	v_fma_f32 v51, v161, s91, v48
	v_fma_f32 v49, v165, s59, v48
	v_fma_f32 v48, v164, s58, v48
	s_waitcnt lgkmcnt(0)
	s_nop 0
	v_mfma_f32_16x16x32_bf16 v[44:47], v[44:47], v[4:7], v[48:51]
	s_nop 2
	ds_read_b128 v[48:51], v97 offset:13888
	s_waitcnt lgkmcnt(0)
	v_mfma_f32_16x16x32_bf16 v[44:47], v[48:51], v[8:11], v[44:47]
	s_cbranch_vccnz .LBB0_930
	v_add_u32_e32 v48, 0xfffff9e1, v1
	v_cmp_lt_i32_e32 vcc, -1, v48
	v_add_u32_e32 v48, 0xfffff9d1, v1
	s_nop 3
	v_cndmask_b32_e32 v44, v194, v44, vcc
	v_cmp_lt_i32_e32 vcc, -1, v48
	v_add_u32_e32 v48, 0xfffff9c1, v1
	s_nop 0
	v_cndmask_b32_e32 v45, v194, v45, vcc
	v_cmp_lt_i32_e32 vcc, -1, v48
	v_add_u32_e32 v48, 0xfffff9b1, v1
	s_nop 0
	v_cndmask_b32_e32 v46, v194, v46, vcc
	v_cmp_lt_i32_e32 vcc, -1, v48
	s_nop 1
	v_cndmask_b32_e32 v47, v194, v47, vcc
.LBB0_930:
	ds_read_b128 v[48:51], v97 offset:16128
	v_add_u32_e32 v59, 0x700, v2
	v_cvt_f32_i32_e32 v59, v59
	s_and_b64 vcc, exec, s[0:1]
	v_mul_f32_e32 v60, v160, v59
	v_fma_f32 v62, v160, s90, v60
	v_fma_f32 v63, v161, s91, v60
	v_fma_f32 v61, v165, s59, v60
	v_fma_f32 v60, v164, s58, v60
	s_waitcnt lgkmcnt(0)
	s_nop 0
	v_mfma_f32_16x16x32_bf16 v[48:51], v[48:51], v[4:7], v[60:63]
	s_nop 2
	ds_read_b128 v[60:63], v97 offset:16192
	s_waitcnt lgkmcnt(0)
	v_mfma_f32_16x16x32_bf16 v[48:51], v[60:63], v[8:11], v[48:51]
	s_cbranch_vccnz .LBB0_932
	v_add_u32_e32 v59, 0xfffff8e1, v1
	v_cmp_lt_i32_e32 vcc, -1, v59
	v_add_u32_e32 v59, 0xfffff8d1, v1
	s_nop 3
	v_cndmask_b32_e32 v48, v194, v48, vcc
	v_cmp_lt_i32_e32 vcc, -1, v59
	v_add_u32_e32 v59, 0xfffff8c1, v1
	s_nop 0
	v_cndmask_b32_e32 v49, v194, v49, vcc
	v_cmp_lt_i32_e32 vcc, -1, v59
	v_add_u32_e32 v59, 0xfffff8b1, v1
	s_nop 0
	v_cndmask_b32_e32 v50, v194, v50, vcc
	v_cmp_lt_i32_e32 vcc, -1, v59
	s_nop 1
	v_cndmask_b32_e32 v51, v194, v51, vcc

; #define LAS __attribute__((address_space(3)))
; __device__ __forceinline__ float bf2f(bf16_t h) { return __uint_as_float((unsigned)h << 16); }
; __device__ __forceinline__ void nsa_phase(LAS unsigned char* lds, const Args& a, const bf16_t* z, const bf16_t* KC, const bf16_t* VCT, const bf16_t* VST, const bf16_t* VWT, bf16_t* A2, int ldo, bool merged) {
;     ...
;         bf16x8 Qf[2][2]; int tq[2]; float gate[2][3];
; #pragma unroll
;         for (int qs = 0; qs < 2; ++qs) {
;             const int ql = qh * 32 + qs * 16 + l15; tq[qs] = t0 + ql;
;             const bf16_t* zr = z + (row0 + ql) * ZLD;
;             Qf[qs][0] = *(const bf16x8*)(zr + ZQ + hq * 64 + g4 * 8);
;             Qf[qs][1] = *(const bf16x8*)(zr + ZQ + hq * 64 + 32 + g4 * 8);
; #pragma unroll
;             for (int br = 0; br < 3; ++br) gate[qs][br] = sigm(bf2f(zr[ZGT + hq * 3 + br]) + gbias[hq * 3 + br]);
;     ...
;             for (int tl = 0; tl < 4; ++tl) {
;                 if (tl <= tlmax) {
; #pragma unroll
;                     for (int s = 0; s < 4; ++s) {
;                         const LAS unsigned char* kp = lds + kcl_off + (tl * 64 + s * 16) * 144;
;                         const bf16x8 k0 = *(const LAS bf16x8*)kp, k1 = *(const LAS bf16x8*)(kp + 64);
;                         const float cb = slope * (float)((tl * 1024 + s * 256 + 64 * g4 + 31) - tq[qs]);
;                         f32x4 zz;
; #pragma unroll
;                         for (int i = 0; i < 4; ++i) zz[i] = fmaf(slope, 16.f * (float)i, cb);
;                         zz = MFMA16(k0, Qf[qs][0], zz);
;                         zz = MFMA16(k1, Qf[qs][1], zz);
;                         if (!((64 * (tl + 1) - 1) <= (4 * qt - 2))) {
; #pragma unroll
;                             for (int i = 0; i < 4; ++i) {
;                                 const int dist = (tq[qs] - 31 - 64 * g4) - (tl * 1024 + s * 256 + 16 * i);
;                                 const bool ok = (dist >= 0) && !(tl == 3 && s == 3 && i == 3 && g4 == 3);
;                                 zz[i] = ok ? zz[i] : -1e30f;
;                             }
;                         }
; #pragma unroll
;                         for (int i = 0; i < 4; ++i) mx = fmaxf(mx, zz[i]);
;                         sc[tl][s] = zz;
;                         __builtin_amdgcn_sched_barrier(0);
;                     }
.LBB0_934:
	s_waitcnt vmcnt(5)
	v_lshlrev_b32_e32 v59, 16, v58
	v_add_f32_e32 v59, v52, v59
	v_mul_f32_e32 v59, 0xbfb8aa3b, v59
	v_exp_f32_e32 v59, v59
	v_and_b32_e32 v58, 0xffff0000, v58
	v_add_f32_e32 v58, v53, v58
	s_waitcnt vmcnt(4)
	v_lshlrev_b32_e32 v57, 16, v57
	v_add_f32_e32 v59, 1.0, v59
	v_rcp_f32_e32 v172, v59
	s_waitcnt vmcnt(1)
	v_lshlrev_b32_e32 v59, 16, v56
	v_add_f32_e32 v52, v52, v59
	v_and_b32_e32 v56, 0xffff0000, v56
	v_mul_f32_e32 v52, 0xbfb8aa3b, v52
	v_add_f32_e32 v53, v53, v56
	s_waitcnt vmcnt(0)
	v_lshlrev_b32_e32 v55, 16, v55
	v_add_f32_e32 v57, v54, v57
	v_exp_f32_e32 v52, v52
	v_mul_f32_e32 v53, 0xbfb8aa3b, v53
	v_add_f32_e32 v54, v54, v55
	v_mul_f32_e32 v58, 0xbfb8aa3b, v58
	v_mul_f32_e32 v57, 0xbfb8aa3b, v57
	v_exp_f32_e32 v53, v53
	v_mul_f32_e32 v54, 0xbfb8aa3b, v54
	v_exp_f32_e32 v58, v58
	v_exp_f32_e32 v57, v57
	v_exp_f32_e32 v54, v54
	v_add_f32_e32 v52, 1.0, v52
	v_rcp_f32_e32 v174, v52
	v_add_f32_e32 v52, 1.0, v53
	v_add_f32_e32 v58, 1.0, v58
	v_add_f32_e32 v57, 1.0, v57
	v_rcp_f32_e32 v200, v52
	v_add_f32_e32 v52, 1.0, v54
	v_rcp_f32_e32 v199, v58
	v_rcp_f32_e32 v198, v57
	v_rcp_f32_e32 v171, v52
	s_cmp_gt_u32 s63, 31
	s_cselect_b64 s[12:13], -1, 0
	s_cmp_lt_u32 s63, 32
	v_mov_b32_e32 v55, 0xf149f2ca
	s_cbranch_scc1 .LBB0_944
	ds_read_b128 v[52:55], v97 offset:18432
	v_add_u32_e32 v56, 0x800, v2
	v_cvt_f32_i32_e32 v60, v56
	ds_read_b128 v[56:59], v97 offset:18496
	v_mov_b32_e32 v161, v160
	s_cmp_lt_u32 s63, 49
	v_mul_f32_e32 v60, v160, v60
	v_fma_f32 v62, v160, s90, v60
	v_fma_f32 v63, v161, s91, v60
	v_fma_f32 v61, v165, s59, v60
	v_fma_f32 v60, v164, s58, v60
	s_cselect_b64 s[8:9], -1, 0
	s_cmp_gt_u32 s63, 48
	s_waitcnt lgkmcnt(1)
	v_mfma_f32_16x16x32_bf16 v[52:55], v[52:55], v[4:7], v[60:63]
	s_waitcnt lgkmcnt(0)
	v_mfma_f32_16x16x32_bf16 v[52:55], v[56:59], v[8:11], v[52:55]
	s_cbranch_scc1 .LBB0_937
	v_add_u32_e32 v56, 0xfffff7e1, v1
	v_cmp_lt_i32_e32 vcc, -1, v56
	v_add_u32_e32 v56, 0xfffff7d1, v1
	s_nop 3
	v_cndmask_b32_e32 v52, v194, v52, vcc
	v_cmp_lt_i32_e32 vcc, -1, v56
	v_add_u32_e32 v56, 0xfffff7c1, v1
	s_nop 0
	v_cndmask_b32_e32 v53, v194, v53, vcc
	v_cmp_lt_i32_e32 vcc, -1, v56
	v_add_u32_e32 v56, 0xfffff7b1, v1
	s_nop 0
	v_cndmask_b32_e32 v54, v194, v54, vcc
	v_cmp_lt_i32_e32 vcc, -1, v56
	s_nop 1
	v_cndmask_b32_e32 v55, v194, v55, vcc
.LBB0_937:
	ds_read_b128 v[56:59], v97 offset:20736
	v_add_u32_e32 v60, 0x900, v2
	v_cvt_f32_i32_e32 v64, v60
	ds_read_b128 v[60:63], v97 offset:20800
	s_andn2_b64 vcc, exec, s[8:9]
	v_mul_f32_e32 v64, v160, v64
	v_fma_f32 v66, v160, s90, v64
	v_fma_f32 v67, v161, s91, v64
	v_fma_f32 v65, v165, s59, v64
	v_fma_f32 v64, v164, s58, v64
	s_waitcnt lgkmcnt(1)
	s_nop 0
	v_mfma_f32_16x16x32_bf16 v[56:59], v[56:59], v[4:7], v[64:67]
	s_waitcnt lgkmcnt(0)
	v_mfma_f32_16x16x32_bf16 v[56:59], v[60:63], v[8:11], v[56:59]
	s_nop 0
	v_cndmask_b32_e64 v64, 0, 1, s[8:9]
	v_cmp_ne_u32_e64 s[0:1], 1, v64
	s_cbranch_vccnz .LBB0_939
	v_add_u32_e32 v60, 0xfffff6e1, v1
	v_cmp_lt_i32_e32 vcc, -1, v60
	v_add_u32_e32 v60, 0xfffff6d1, v1
	s_nop 0
	v_cndmask_b32_e32 v56, v194, v56, vcc
	v_cmp_lt_i32_e32 vcc, -1, v60
	v_add_u32_e32 v60, 0xfffff6c1, v1
	s_nop 0
	v_cndmask_b32_e32 v57, v194, v57, vcc
	v_cmp_lt_i32_e32 vcc, -1, v60
	v_add_u32_e32 v60, 0xfffff6b1, v1
	s_nop 0
	v_cndmask_b32_e32 v58, v194, v58, vcc
	v_cmp_lt_i32_e32 vcc, -1, v60
	s_nop 1
	v_cndmask_b32_e32 v59, v194, v59, vcc
.LBB0_939:
	ds_read_b128 v[60:63], v97 offset:23040
	v_add_u32_e32 v64, 0xa00, v2
	v_cvt_f32_i32_e32 v64, v64
	v_mov_b32_e32 v161, v160
	s_and_b64 vcc, exec, s[0:1]
	v_mul_f32_e32 v64, v160, v64
	v_fma_f32 v66, v160, s90, v64
	v_fma_f32 v67, v161, s91, v64
	v_fma_f32 v65, v165, s59, v64
	v_fma_f32 v64, v164, s58, v64
	s_waitcnt lgkmcnt(0)
	s_nop 0
	v_mfma_f32_16x16x32_bf16 v[60:63], v[60:63], v[4:7], v[64:67]
	s_nop 2
	ds_read_b128 v[64:67], v97 offset:23104
	s_waitcnt lgkmcnt(0)
	v_mfma_f32_16x16x32_bf16 v[60:63], v[64:67], v[8:11], v[60:63]
	s_cbranch_vccnz .LBB0_941
	v_add_u32_e32 v64, 0xfffff5e1, v1
	v_cmp_lt_i32_e32 vcc, -1, v64
	v_add_u32_e32 v64, 0xfffff5d1, v1
	s_nop 3
	v_cndmask_b32_e32 v60, v194, v60, vcc
	v_cmp_lt_i32_e32 vcc, -1, v64
	v_add_u32_e32 v64, 0xfffff5c1, v1
	s_nop 0
	v_cndmask_b32_e32 v61, v194, v61, vcc
	v_cmp_lt_i32_e32 vcc, -1, v64
	v_add_u32_e32 v64, 0xfffff5b1, v1
	s_nop 0
	v_cndmask_b32_e32 v62, v194, v62, vcc
	v_cmp_lt_i32_e32 vcc, -1, v64
	s_nop 1
	v_cndmask_b32_e32 v63, v194, v63, vcc
.LBB0_941:
	ds_read_b128 v[64:67], v97 offset:25344
	v_add_u32_e32 v68, 0xb00, v2
	v_cvt_f32_i32_e32 v68, v68
	s_and_b64 vcc, exec, s[0:1]
	v_mul_f32_e32 v68, v160, v68
	v_fma_f32 v70, v160, s90, v68
	v_fma_f32 v71, v161, s91, v68
	v_fma_f32 v69, v165, s59, v68
	v_fma_f32 v68, v164, s58, v68
	s_waitcnt lgkmcnt(0)
	s_nop 0
	v_mfma_f32_16x16x32_bf16 v[64:67], v[64:67], v[4:7], v[68:71]
	s_nop 2
	ds_read_b128 v[68:71], v97 offset:25408
	s_waitcnt lgkmcnt(0)
	v_mfma_f32_16x16x32_bf16 v[72:75], v[68:71], v[8:11], v[64:67]
	s_cbranch_vccnz .LBB0_943
	s_nop 1
	v_add_u32_e32 v64, 0xfffff4e1, v1
	v_cmp_lt_i32_e32 vcc, -1, v64
	v_add_u32_e32 v64, 0xfffff4d1, v1
	s_nop 1
	v_cndmask_b32_e32 v72, v194, v72, vcc
	v_cmp_lt_i32_e32 vcc, -1, v64
	v_add_u32_e32 v64, 0xfffff4c1, v1
	s_nop 0
	v_cndmask_b32_e32 v73, v194, v73, vcc
	v_cmp_lt_i32_e32 vcc, -1, v64
	v_add_u32_e32 v64, 0xfffff4b1, v1
	s_nop 0
	v_cndmask_b32_e32 v74, v194, v74, vcc
	v_cmp_lt_i32_e32 vcc, -1, v64
	s_nop 1
	v_cndmask_b32_e32 v75, v194, v75, vcc

; #define LAS __attribute__((address_space(3)))
; #define MFMA16(a, b, c) __builtin_amdgcn_mfma_f32_16x16x32_bf16(a, b, c, 0, 0, 0)
; __device__ __forceinline__ void nsa_phase(LAS unsigned char* lds, const Args& a, const bf16_t* z, const bf16_t* KC, const bf16_t* VCT, const bf16_t* VST, const bf16_t* VWT, bf16_t* A2, int ldo, bool merged) {
;     ...
;             for (int tl = 0; tl < 4; ++tl) {
;                 if (tl <= tlmax) {
; #pragma unroll
;                     for (int s = 0; s < 4; ++s) {
;                         const LAS unsigned char* kp = lds + kcl_off + (tl * 64 + s * 16) * 144;
;                         const bf16x8 k0 = *(const LAS bf16x8*)kp, k1 = *(const LAS bf16x8*)(kp + 64);
;                         const float cb = slope * (float)((tl * 1024 + s * 256 + 64 * g4 + 31) - tq[qs]);
;                         f32x4 zz;
; #pragma unroll
;                         for (int i = 0; i < 4; ++i) zz[i] = fmaf(slope, 16.f * (float)i, cb);
;                         zz = MFMA16(k0, Qf[qs][0], zz);
;                         zz = MFMA16(k1, Qf[qs][1], zz);
;                         if (!((64 * (tl + 1) - 1) <= (4 * qt - 2))) {
; #pragma unroll
;                             for (int i = 0; i < 4; ++i) {
;                                 const int dist = (tq[qs] - 31 - 64 * g4) - (tl * 1024 + s * 256 + 16 * i);
;                                 const bool ok = (dist >= 0) && !(tl == 3 && s == 3 && i == 3 && g4 == 3);
;                                 zz[i] = ok ? zz[i] : -1e30f;
;                             }
;                         }
; #pragma unroll
;                         for (int i = 0; i < 4; ++i) mx = fmaxf(mx, zz[i]);
;                         sc[tl][s] = zz;
;                         __builtin_amdgcn_sched_barrier(0);
;                     }
;                 } else {
; #pragma unroll
;                     for (int s = 0; s < 4; ++s) sc[tl][s] = (f32x4){-1e30f, -1e30f, -1e30f, -1e30f};
;                 }
;             }
;             mx = fmaxf(mx, __shfl_xor(mx, 16)); mx = fmaxf(mx, __shfl_xor(mx, 32));
.LBB0_945:
	s_and_b32 s8, s63, 48
	s_cmp_eq_u32 s8, 48
	s_cselect_b64 s[0:1], -1, 0
	s_cmp_lg_u32 s8, 48
	s_cselect_b64 s[18:19], -1, 0
	v_cmp_ne_u32_e64 s[14:15], 3, v136
	v_mov_b32_e32 v115, 0xf149f2ca
	s_and_b64 vcc, exec, s[18:19]
	s_cbranch_vccnz .LBB0_947
	ds_read_b128 v[64:67], v97 offset:27648
	v_add_u32_e32 v68, 0xc00, v2
	v_cvt_f32_i32_e32 v76, v68
	ds_read_b128 v[68:71], v97 offset:27712
	v_mov_b32_e32 v161, v160
	v_mul_f32_e32 v76, v160, v76
	v_fma_f32 v78, v160, s90, v76
	v_fma_f32 v79, v161, s91, v76
	v_fma_f32 v77, v165, s59, v76
	v_fma_f32 v76, v164, s58, v76
	s_waitcnt lgkmcnt(1)
	s_nop 0
	v_mfma_f32_16x16x32_bf16 v[64:67], v[64:67], v[4:7], v[76:79]
	s_waitcnt lgkmcnt(0)
	v_mfma_f32_16x16x32_bf16 v[64:67], v[68:71], v[8:11], v[64:67]
	s_nop 0
	v_add_u32_e32 v76, 0xfffff3e1, v1
	v_add_u32_e32 v77, 0xfffff3d1, v1
	v_cmp_lt_i32_e32 vcc, -1, v76
	v_add_u32_e32 v78, 0xfffff3c1, v1
	s_nop 2
	v_cndmask_b32_e32 v100, v194, v64, vcc
	v_cmp_lt_i32_e32 vcc, -1, v77
	v_add_u32_e32 v64, 0xfffff3b1, v1
	s_nop 0
	v_cndmask_b32_e32 v101, v194, v65, vcc
	v_cmp_lt_i32_e32 vcc, -1, v78
	v_max3_f32 v3, v3, v100, v101
	s_nop 0
	v_cndmask_b32_e32 v102, v194, v66, vcc
	v_cmp_lt_i32_e32 vcc, -1, v64
	s_nop 1
	v_cndmask_b32_e32 v103, v194, v67, vcc
	v_max3_f32 v3, v3, v102, v103
	ds_read_b128 v[64:67], v97 offset:29952
	v_add_u32_e32 v68, 0xd00, v2
	v_cvt_f32_i32_e32 v76, v68
	ds_read_b128 v[68:71], v97 offset:30016
	v_mul_f32_e32 v76, v160, v76
	v_fma_f32 v78, v160, s90, v76
	v_fma_f32 v79, v161, s91, v76
	v_fma_f32 v77, v165, s59, v76
	v_fma_f32 v76, v164, s58, v76
	s_waitcnt lgkmcnt(1)
	s_nop 0
	v_mfma_f32_16x16x32_bf16 v[64:67], v[64:67], v[4:7], v[76:79]
	s_waitcnt lgkmcnt(0)
	v_mfma_f32_16x16x32_bf16 v[64:67], v[68:71], v[8:11], v[64:67]
	s_nop 0
	v_add_u32_e32 v76, 0xfffff2e1, v1
	v_add_u32_e32 v77, 0xfffff2d1, v1
	v_cmp_lt_i32_e32 vcc, -1, v76
	v_add_u32_e32 v78, 0xfffff2c1, v1
	s_nop 2
	v_cndmask_b32_e32 v106, v194, v64, vcc
	v_cmp_lt_i32_e32 vcc, -1, v77
	v_add_u32_e32 v64, 0xfffff2b1, v1
	s_nop 0
	v_cndmask_b32_e32 v107, v194, v65, vcc
	v_cmp_lt_i32_e32 vcc, -1, v78
	v_max3_f32 v3, v3, v106, v107
	s_nop 0
	v_cndmask_b32_e32 v108, v194, v66, vcc
	v_cmp_lt_i32_e32 vcc, -1, v64
	s_nop 1
	v_cndmask_b32_e32 v109, v194, v67, vcc
	v_max3_f32 v3, v3, v108, v109
	ds_read_b128 v[64:67], v97 offset:32256
	v_add_u32_e32 v68, 0xe00, v2
	v_cvt_f32_i32_e32 v76, v68
	ds_read_b128 v[68:71], v97 offset:32320
	v_mul_f32_e32 v76, v160, v76
	v_fma_f32 v78, v160, s90, v76
	v_fma_f32 v79, v161, s91, v76
	v_fma_f32 v77, v165, s59, v76
	v_fma_f32 v76, v164, s58, v76
	s_waitcnt lgkmcnt(1)
	s_nop 0
	v_mfma_f32_16x16x32_bf16 v[64:67], v[64:67], v[4:7], v[76:79]
	s_waitcnt lgkmcnt(0)
	v_mfma_f32_16x16x32_bf16 v[64:67], v[68:71], v[8:11], v[64:67]
	s_nop 0
	v_add_u32_e32 v76, 0xfffff1e1, v1
	v_add_u32_e32 v77, 0xfffff1d1, v1
	v_cmp_lt_i32_e32 vcc, -1, v76
	v_add_u32_e32 v78, 0xfffff1c1, v1
	s_nop 2
	v_cndmask_b32_e32 v110, v194, v64, vcc
	v_cmp_lt_i32_e32 vcc, -1, v77
	v_add_u32_e32 v64, 0xfffff1b1, v1
	s_nop 0
	v_cndmask_b32_e32 v111, v194, v65, vcc
	v_cmp_lt_i32_e32 vcc, -1, v78
	v_max3_f32 v3, v3, v110, v111
	s_nop 0
	v_cndmask_b32_e32 v113, v194, v66, vcc
	v_cmp_lt_i32_e32 vcc, -1, v64
	s_nop 1
	v_cndmask_b32_e32 v114, v194, v67, vcc
	v_max3_f32 v3, v3, v113, v114
	ds_read_b128 v[64:67], v97 offset:34560
	ds_read_b128 v[68:71], v97 offset:34624
	v_add_u32_e32 v2, 0xf00, v2
	v_cvt_f32_i32_e32 v2, v2
	v_mul_f32_e32 v2, v160, v2
	v_fma_f32 v78, v160, s90, v2
	v_fma_f32 v79, v161, s91, v2
	v_fma_f32 v76, v164, s58, v2
	v_fma_f32 v77, v165, s59, v2
	v_add_u32_e32 v2, 0xfffff0e1, v1
	v_cmp_lt_i32_e32 vcc, -1, v2
	s_waitcnt lgkmcnt(1)
	v_mfma_f32_16x16x32_bf16 v[64:67], v[64:67], v[4:7], v[76:79]
	s_waitcnt lgkmcnt(0)
	v_mfma_f32_16x16x32_bf16 v[64:67], v[68:71], v[8:11], v[64:67]
	s_nop 0
	v_add_u32_e32 v76, 0xfffff0d1, v1
	v_add_u32_e32 v77, 0xfffff0c1, v1
	v_add_u32_e32 v1, 0xfffff0b1, v1
	s_nop 3
	v_cndmask_b32_e32 v115, v194, v64, vcc
	v_cmp_lt_i32_e32 vcc, -1, v76
	s_nop 1
	v_cndmask_b32_e32 v118, v194, v65, vcc
	v_cmp_lt_i32_e32 vcc, -1, v77
	s_nop 1
	v_cndmask_b32_e32 v120, v194, v66, vcc
	v_cmp_lt_i32_e32 vcc, -1, v1
	s_and_b64 vcc, vcc, s[14:15]
	v_max3_f32 v1, v3, v115, v118
	v_cndmask_b32_e32 v121, v194, v67, vcc
	v_max3_f32 v3, v1, v120, v121
	s_branch .LBB0_948

; #define LAS __attribute__((address_space(3)))
; __device__ __forceinline__ void nsa_phase(LAS unsigned char* lds, const Args& a, const bf16_t* z, const bf16_t* KC, const bf16_t* VCT, const bf16_t* VST, const bf16_t* VWT, bf16_t* A2, int ldo, bool merged) {
;     ...
;             ps += __shfl_xor(ps, 16); ps += __shfl_xor(ps, 32);
;             const float inv = ps > 0.f ? 1.f / ps : 0.f;
;             unsigned imp_off = (unsigned)((hr * 64 + qh * 32 + qs * 16 + l15) * 65 + g4) * 4u; asm volatile("" : "+v"(imp_off));
;             LAS float* impw = (LAS float*)(lds + NS_IMP + imp_off);
;             float prev3 = 0.f;
; #pragma unroll
;             for (int tl = 0; tl < 4; ++tl) {
;                 if (tl <= tlmax) {
; #pragma unroll
;                     for (int s = 0; s < 4; ++s) {
;                         f32x4 p = sc[tl][s] * inv; sc[tl][s] = p;
;                         const float from_same = __shfl(p[3], (lane + 48) & 63);
;                         const float from_prev = __shfl(prev3, (lane + 48) & 63);
;                         const float p3m = (g4 > 0) ? from_same : from_prev;
;                         impw[tl * 16 + s * 4] = p3m + 2.f * (p[0] + p[1] + p[2]) + p[3];
;                         prev3 = p[3];
;                     }
;                 } else {
; #pragma unroll
;                     for (int s = 0; s < 4; ++s) {
;                         const float from_prev = __shfl(prev3, (lane + 48) & 63);
;                         impw[tl * 16 + s * 4] = (g4 > 0) ? 0.f : from_prev;
;                         prev3 = 0.f;
;                     }
;                 }
;             }
.LBB0_955:
	ds_bpermute_b32 v1, v201, v123
	v_readlane_b32 s0, v247, 38
	v_cmp_lt_i32_e64 s[12:13], 0, v136
	s_waitcnt lgkmcnt(0)
	v_add_f32_e32 v1, v123, v1
	ds_bpermute_b32 v3, v202, v1
	v_add_u32_e32 v2, s0, v170
	v_lshl_add_u32 v118, v2, 6, v2
	v_add_lshl_u32 v52, v118, v136, 2
	s_waitcnt lgkmcnt(0)
	v_add_f32_e32 v1, v1, v3
	v_div_scale_f32 v3, s[0:1], v1, v1, 1.0
	v_rcp_f32_e32 v53, v3
	v_add_u32_e32 v2, 0, v52
	v_add_u32_e32 v54, 0x11400, v2
	v_div_scale_f32 v2, vcc, 1.0, v1, 1.0
	v_fma_f32 v55, -v3, v53, 1.0
	v_fmac_f32_e32 v53, v55, v53
	v_mul_f32_e32 v55, v2, v53
	v_fma_f32 v56, -v3, v55, v2
	v_fmac_f32_e32 v55, v56, v53
	v_fma_f32 v2, -v3, v55, v2
	v_div_fmas_f32 v2, v2, v53, v55
	v_div_fixup_f32 v2, v2, v1, 1.0
	v_cmp_lt_f32_e32 vcc, 0, v1
	s_mov_b64 s[0:1], -1
	s_nop 0
	v_cndmask_b32_e32 v102, 0, v2, vcc
	v_mov_b32_e32 v103, v102
	v_pk_mul_f32 v[2:3], v[98:99], v[102:103] op_sel_hi:[1,0]
	ds_bpermute_b32 v1, v193, v3
	v_pk_mul_f32 v[98:99], v[104:105], v[102:103] op_sel_hi:[1,0]
	v_pk_mul_f32 v[100:101], v[94:95], v[102:103] op_sel_hi:[1,0]
	ds_bpermute_b32 v56, v193, v99
	v_add_f32_e32 v53, v100, v101
	s_waitcnt lgkmcnt(1)
	v_cndmask_b32_e64 v55, 0, v1, s[12:13]
	v_add_f32_e32 v53, v2, v53
	v_fmac_f32_e32 v55, 2.0, v53
	v_pk_mul_f32 v[114:115], v[92:93], v[102:103] op_sel_hi:[1,0]
	v_add_f32_e32 v53, v3, v55
	v_add_f32_e32 v55, v114, v115
	v_pk_mul_f32 v[104:105], v[86:87], v[102:103] op_sel_hi:[1,0]
	s_waitcnt lgkmcnt(0)
	v_cndmask_b32_e64 v1, v1, v56, s[12:13]
	v_add_f32_e32 v55, v98, v55
	ds_bpermute_b32 v57, v193, v105
	v_pk_mul_f32 v[108:109], v[82:83], v[102:103] op_sel_hi:[1,0]
	v_fmac_f32_e32 v1, 2.0, v55
	ds_bpermute_b32 v55, v193, v109
	v_add_f32_e32 v1, v99, v1
	v_pk_mul_f32 v[106:107], v[84:85], v[102:103] op_sel_hi:[1,0]
	ds_write2_b32 v54, v53, v1 offset1:4
	v_add_f32_e32 v53, v106, v107
	s_waitcnt lgkmcnt(2)
	v_cndmask_b32_e64 v1, v56, v57, s[12:13]
	v_add_f32_e32 v53, v104, v53
	v_pk_mul_f32 v[110:111], v[80:81], v[102:103] op_sel_hi:[1,0]
	v_fmac_f32_e32 v1, 2.0, v53
	s_waitcnt lgkmcnt(1)
	v_cndmask_b32_e64 v53, v57, v55, s[12:13]
	v_add_f32_e32 v55, v110, v111
	v_add_f32_e32 v55, v108, v55
	v_fmac_f32_e32 v53, 2.0, v55
	v_add_f32_e32 v1, v105, v1
	v_add_f32_e32 v53, v109, v53
	ds_write2_b32 v54, v1, v53 offset0:8 offset1:12
	s_and_b64 vcc, exec, s[10:11]
	v_add_u32_e32 v1, s33, v52
	s_cbranch_vccnz .LBB0_957
	v_mov_b32_e32 v52, v102
	v_mov_b32_e32 v53, v102
	v_pk_mul_f32 v[82:83], v[66:67], v[52:53]
	ds_bpermute_b32 v54, v193, v109
	ds_bpermute_b32 v60, v193, v83
	v_pk_mul_f32 v[86:87], v[70:71], v[52:53]
	v_pk_mul_f32 v[58:59], v[78:79], v[52:53]
	v_pk_mul_f32 v[80:81], v[64:65], v[102:103]
	ds_bpermute_b32 v61, v193, v87
	ds_bpermute_b32 v72, v193, v59
	v_add_f32_e32 v55, v80, v81
	s_waitcnt lgkmcnt(2)
	v_cndmask_b32_e64 v54, v54, v60, s[12:13]
	v_add_f32_e32 v55, v82, v55
	v_fmac_f32_e32 v54, 2.0, v55
	v_add_f32_e32 v54, v83, v54
	v_pk_mul_f32 v[84:85], v[68:69], v[102:103]
	v_pk_mul_f32 v[56:57], v[76:77], v[102:103]
	ds_write_b32 v1, v54 offset:64
	s_waitcnt lgkmcnt(1)
	v_cndmask_b32_e64 v55, v61, v72, s[12:13]
	v_cndmask_b32_e64 v54, v60, v61, s[12:13]
	v_mov_b32_e32 v60, v84
	v_mov_b32_e32 v61, v56
	v_mov_b32_e32 v62, v85
	v_mov_b32_e32 v63, v57
	v_pk_add_f32 v[60:61], v[60:61], v[62:63]
	v_mov_b32_e32 v62, v86
	v_mov_b32_e32 v63, v58
	v_pk_add_f32 v[60:61], v[62:63], v[60:61]
	v_pk_mul_f32 v[94:95], v[90:91], v[52:53]
	v_fma_f32 v54, v60, 2.0, v54
	v_fma_f32 v55, v61, 2.0, v55
	ds_bpermute_b32 v60, v193, v95
	v_mov_b32_e32 v52, v87
	v_mov_b32_e32 v53, v59
	v_pk_mul_f32 v[92:93], v[88:89], v[102:103]
	v_pk_add_f32 v[52:53], v[52:53], v[54:55]
	v_add_f32_e32 v55, v92, v93
	s_waitcnt lgkmcnt(0)
	v_cndmask_b32_e64 v54, v72, v60, s[12:13]
	v_add_f32_e32 v55, v94, v55
	v_fmac_f32_e32 v54, 2.0, v55
	v_mov_b64_e32 v[72:73], v[92:93]
	v_add_f32_e32 v54, v95, v54
	s_mov_b64 s[0:1], 0
	v_mov_b64_e32 v[74:75], v[94:95]

; __device__ __forceinline__ void nsa_phase(LAS unsigned char* lds, const Args& a, const bf16_t* z, const bf16_t* KC, const bf16_t* VCT, const bf16_t* VST, const bf16_t* VWT, bf16_t* A2, int ldo, bool merged) {
;     ...
;             for (int tl = 0; tl < 4; ++tl) {
;                 if (tl <= tlmax) {
; #pragma unroll
;                     for (int s = 0; s < 4; ++s) {
;                         f32x4 p = sc[tl][s] * inv; sc[tl][s] = p;
;                         const float from_same = __shfl(p[3], (lane + 48) & 63);
;                         const float from_prev = __shfl(prev3, (lane + 48) & 63);
;                         const float p3m = (g4 > 0) ? from_same : from_prev;
;                         impw[tl * 16 + s * 4] = p3m + 2.f * (p[0] + p[1] + p[2]) + p[3];
;                         prev3 = p[3];
;                     }
;                 } else {
; #pragma unroll
;                     for (int s = 0; s < 4; ++s) {
;                         const float from_prev = __shfl(prev3, (lane + 48) & 63);
;                         impw[tl * 16 + s * 4] = (g4 > 0) ? 0.f : from_prev;
;                         prev3 = 0.f;
;                     }
;                 }
;             }
.LBB0_959:
	s_and_b64 vcc, exec, s[8:9]
	s_mov_b64 s[0:1], -1
	ds_write2_b32 v1, v52, v53 offset0:20 offset1:24
	ds_write_b32 v1, v54 offset:112
	s_cbranch_vccnz .LBB0_961
	v_mov_b32_e32 v60, v102
	v_mov_b32_e32 v61, v102
	v_pk_mul_f32 v[66:67], v[22:23], v[60:61]
	ds_bpermute_b32 v52, v193, v95
	ds_bpermute_b32 v62, v193, v67
	v_pk_mul_f32 v[64:65], v[20:21], v[102:103]
	v_pk_mul_f32 v[70:71], v[26:27], v[60:61]
	v_pk_mul_f32 v[54:55], v[30:31], v[60:61]
	v_add_f32_e32 v53, v64, v65
	ds_bpermute_b32 v76, v193, v71
	ds_bpermute_b32 v90, v193, v55
	s_waitcnt lgkmcnt(2)
	v_cndmask_b32_e64 v52, v52, v62, s[12:13]
	v_add_f32_e32 v53, v66, v53
	v_fmac_f32_e32 v52, 2.0, v53
	v_add_f32_e32 v52, v67, v52
	ds_write_b32 v1, v52 offset:128
	v_pk_mul_f32 v[68:69], v[24:25], v[102:103]
	v_pk_mul_f32 v[52:53], v[28:29], v[102:103]
	s_waitcnt lgkmcnt(1)
	v_cndmask_b32_e64 v63, v76, v90, s[12:13]
	v_cndmask_b32_e64 v62, v62, v76, s[12:13]
	v_mov_b32_e32 v76, v68
	v_mov_b32_e32 v77, v52
	v_mov_b32_e32 v78, v69
	v_mov_b32_e32 v79, v53
	v_pk_add_f32 v[76:77], v[76:77], v[78:79]
	v_mov_b32_e32 v78, v70
	v_mov_b32_e32 v79, v54
	v_pk_add_f32 v[76:77], v[78:79], v[76:77]
	v_pk_mul_f32 v[78:79], v[34:35], v[60:61]
	ds_bpermute_b32 v91, v193, v79
	v_fma_f32 v62, v76, 2.0, v62
	v_fma_f32 v63, v77, 2.0, v63
	v_mov_b32_e32 v60, v71
	v_mov_b32_e32 v61, v55
	v_pk_mul_f32 v[76:77], v[32:33], v[102:103]
	v_pk_add_f32 v[88:89], v[60:61], v[62:63]
	v_add_f32_e32 v61, v76, v77
	s_waitcnt lgkmcnt(0)
	v_cndmask_b32_e64 v60, v90, v91, s[12:13]
	v_add_f32_e32 v61, v78, v61
	v_fmac_f32_e32 v60, 2.0, v61
	v_add_f32_e32 v90, v79, v60
	v_mov_b64_e32 v[60:61], v[76:77]
	s_mov_b64 s[0:1], 0
	v_mov_b64_e32 v[62:63], v[78:79]

; __device__ __forceinline__ void nsa_phase(LAS unsigned char* lds, const Args& a, const bf16_t* z, const bf16_t* KC, const bf16_t* VCT, const bf16_t* VST, const bf16_t* VWT, bf16_t* A2, int ldo, bool merged) {
;     ...
;             for (int tl = 0; tl < 4; ++tl) {
;                 if (tl <= tlmax) {
; #pragma unroll
;                     for (int s = 0; s < 4; ++s) {
;                         f32x4 p = sc[tl][s] * inv; sc[tl][s] = p;
;                         const float from_same = __shfl(p[3], (lane + 48) & 63);
;                         const float from_prev = __shfl(prev3, (lane + 48) & 63);
;                         const float p3m = (g4 > 0) ? from_same : from_prev;
;                         impw[tl * 16 + s * 4] = p3m + 2.f * (p[0] + p[1] + p[2]) + p[3];
;                         prev3 = p[3];
;                     }
;                 } else {
; #pragma unroll
;                     for (int s = 0; s < 4; ++s) {
;                         const float from_prev = __shfl(prev3, (lane + 48) & 63);
;                         impw[tl * 16 + s * 4] = (g4 > 0) ? 0.f : from_prev;
;                         prev3 = 0.f;
;                     }
;                 }
;             }
.LBB0_965:
	s_andn2_b64 vcc, exec, s[0:1]
	v_mov_b32_e32 v23, 0
	s_cbranch_vccnz .LBB0_967
	v_mov_b32_e32 v20, v102
	v_mov_b32_e32 v21, v102
	v_pk_mul_f32 v[46:47], v[46:47], v[20:21]
	ds_bpermute_b32 v22, v193, v79
	ds_bpermute_b32 v23, v193, v47
	v_pk_mul_f32 v[50:51], v[50:51], v[20:21]
	v_pk_mul_f32 v[38:39], v[38:39], v[20:21]
	ds_bpermute_b32 v26, v193, v51
	ds_bpermute_b32 v30, v193, v39
	v_pk_mul_f32 v[44:45], v[44:45], v[102:103]
	s_waitcnt lgkmcnt(2)
	v_cndmask_b32_e64 v22, v22, v23, s[12:13]
	v_add_f32_e32 v24, v44, v45
	v_add_f32_e32 v24, v46, v24
	v_pk_mul_f32 v[48:49], v[48:49], v[102:103]
	v_pk_mul_f32 v[36:37], v[36:37], v[102:103]
	v_pk_mul_f32 v[42:43], v[42:43], v[20:21]
	v_fmac_f32_e32 v22, 2.0, v24
	s_waitcnt lgkmcnt(0)
	v_cndmask_b32_e64 v25, v26, v30, s[12:13]
	v_cndmask_b32_e64 v24, v23, v26, s[12:13]
	v_mov_b32_e32 v26, v48
	v_mov_b32_e32 v27, v36
	v_mov_b32_e32 v28, v49
	v_mov_b32_e32 v29, v37
	ds_bpermute_b32 v23, v193, v43
	v_pk_add_f32 v[26:27], v[26:27], v[28:29]
	v_mov_b32_e32 v28, v50
	v_mov_b32_e32 v29, v38
	v_pk_add_f32 v[26:27], v[28:29], v[26:27]
	v_mov_b32_e32 v20, v51
	v_fma_f32 v24, v26, 2.0, v24
	v_fma_f32 v25, v27, 2.0, v25
	v_mov_b32_e32 v21, v39
	v_pk_mul_f32 v[40:41], v[40:41], v[102:103]
	v_pk_add_f32 v[20:21], v[20:21], v[24:25]
	v_add_f32_e32 v24, v40, v41
	s_waitcnt lgkmcnt(0)
	v_cndmask_b32_e64 v23, v30, v23, s[12:13]
	v_add_f32_e32 v24, v42, v24
	v_fmac_f32_e32 v23, 2.0, v24
	v_add_f32_e32 v22, v47, v22
	v_add_f32_e32 v23, v43, v23
	s_branch .LBB0_968

; #define LAS __attribute__((address_space(3)))
; #define MFMA16(a, b, c) __builtin_amdgcn_mfma_f32_16x16x32_bf16(a, b, c, 0, 0, 0)
; __device__ __forceinline__ void nsa_phase(LAS unsigned char* lds, const Args& a, const bf16_t* z, const bf16_t* KC, const bf16_t* VCT, const bf16_t* VST, const bf16_t* VWT, bf16_t* A2, int ldo, bool merged) {
;     ...
;             for (int tl = 0; tl < 4; ++tl) {
;                 if (tl <= tlmax) {
; #pragma unroll
;                     for (int s = 0; s < 4; ++s) {
;                         const LAS unsigned char* kp = lds + kcl_off + (tl * 64 + s * 16) * 144;
;                         const bf16x8 k0 = *(const LAS bf16x8*)kp, k1 = *(const LAS bf16x8*)(kp + 64);
;                         const float cb = slope * (float)((tl * 1024 + s * 256 + 64 * g4 + 31) - tq[qs]);
;                         f32x4 zz;
; #pragma unroll
;                         for (int i = 0; i < 4; ++i) zz[i] = fmaf(slope, 16.f * (float)i, cb);
;                         zz = MFMA16(k0, Qf[qs][0], zz);
;                         zz = MFMA16(k1, Qf[qs][1], zz);
;                         if (!((64 * (tl + 1) - 1) <= (4 * qt - 2))) {
; #pragma unroll
;                             for (int i = 0; i < 4; ++i) {
;                                 const int dist = (tq[qs] - 31 - 64 * g4) - (tl * 1024 + s * 256 + 16 * i);
;                                 const bool ok = (dist >= 0) && !(tl == 3 && s == 3 && i == 3 && g4 == 3);
;                                 zz[i] = ok ? zz[i] : -1e30f;
;                             }
;                         }
; #pragma unroll
;                         for (int i = 0; i < 4; ++i) mx = fmaxf(mx, zz[i]);
;                         sc[tl][s] = zz;
;                         __builtin_amdgcn_sched_barrier(0);
;                     }
.LBB0_975:
	ds_read_b128 v[36:39], v97
	v_add_u32_e32 v139, s22, v96
	v_sub_u32_e32 v1, v117, v139
	v_cvt_f32_i32_e32 v2, v1
	v_mov_b32_e32 v161, v160
	s_and_b64 vcc, exec, s[16:17]
	v_mul_f32_e32 v2, v160, v2
	v_fma_f32 v42, v160, s90, v2
	v_fma_f32 v43, v161, s91, v2
	v_fma_f32 v40, v164, s58, v2
	v_fma_f32 v41, v165, s59, v2
	v_sub_u32_e32 v2, v139, v116
	s_waitcnt lgkmcnt(0)
	v_mfma_f32_16x16x32_bf16 v[36:39], v[36:39], v[12:15], v[40:43]
	s_nop 2
	ds_read_b128 v[40:43], v97 offset:64
	s_waitcnt lgkmcnt(0)
	v_mfma_f32_16x16x32_bf16 v[36:39], v[40:43], v[16:19], v[36:39]
	s_cbranch_vccnz .LBB0_977
	v_subrev_u32_e32 v3, 31, v2
	v_cmp_lt_i32_e32 vcc, -1, v3
	v_subrev_u32_e32 v3, 47, v2
	s_nop 3
	v_cndmask_b32_e32 v36, v194, v36, vcc
	v_cmp_lt_i32_e32 vcc, -1, v3
	v_subrev_u32_e32 v3, 63, v2
	s_nop 0
	v_cndmask_b32_e32 v37, v194, v37, vcc
	v_cmp_lt_i32_e32 vcc, -1, v3
	v_add_u32_e32 v3, 0xffffffb1, v2
	s_nop 0
	v_cndmask_b32_e32 v38, v194, v38, vcc
	v_cmp_lt_i32_e32 vcc, -1, v3
	s_nop 1
	v_cndmask_b32_e32 v39, v194, v39, vcc
.LBB0_977:
	ds_read_b128 v[40:43], v97 offset:2304
	v_add_u32_e32 v3, 0x100, v1
	v_cvt_f32_i32_e32 v3, v3
	s_and_b64 vcc, exec, s[16:17]
	v_mul_f32_e32 v44, v160, v3
	v_fma_f32 v46, v160, s90, v44
	v_fma_f32 v47, v161, s91, v44
	v_fma_f32 v45, v165, s59, v44
	v_fma_f32 v44, v164, s58, v44
	s_waitcnt lgkmcnt(0)
	s_nop 0
	v_mfma_f32_16x16x32_bf16 v[40:43], v[40:43], v[12:15], v[44:47]
	s_nop 2
	ds_read_b128 v[44:47], v97 offset:2368
	s_waitcnt lgkmcnt(0)
	v_mfma_f32_16x16x32_bf16 v[40:43], v[44:47], v[16:19], v[40:43]
	s_cbranch_vccnz .LBB0_979
	v_add_u32_e32 v3, 0xfffffee1, v2
	v_cmp_lt_i32_e32 vcc, -1, v3
	v_add_u32_e32 v3, 0xfffffed1, v2
	s_nop 3
	v_cndmask_b32_e32 v40, v194, v40, vcc
	v_cmp_lt_i32_e32 vcc, -1, v3
	v_add_u32_e32 v3, 0xfffffec1, v2
	s_nop 0
	v_cndmask_b32_e32 v41, v194, v41, vcc
	v_cmp_lt_i32_e32 vcc, -1, v3
	v_add_u32_e32 v3, 0xfffffeb1, v2
	s_nop 0
	v_cndmask_b32_e32 v42, v194, v42, vcc
	v_cmp_lt_i32_e32 vcc, -1, v3
	s_nop 1
	v_cndmask_b32_e32 v43, v194, v43, vcc
.LBB0_979:
	ds_read_b128 v[44:47], v97 offset:4608
	v_add_u32_e32 v3, 0x200, v1
	v_cvt_f32_i32_e32 v3, v3
	v_mov_b32_e32 v161, v160
	s_and_b64 vcc, exec, s[16:17]
	v_mul_f32_e32 v48, v160, v3
	v_fma_f32 v50, v160, s90, v48
	v_fma_f32 v51, v161, s91, v48
	v_fma_f32 v49, v165, s59, v48
	v_fma_f32 v48, v164, s58, v48
	s_waitcnt lgkmcnt(0)
	s_nop 0
	v_mfma_f32_16x16x32_bf16 v[44:47], v[44:47], v[12:15], v[48:51]
	s_nop 2
	ds_read_b128 v[48:51], v97 offset:4672
	s_waitcnt lgkmcnt(0)
	v_mfma_f32_16x16x32_bf16 v[44:47], v[48:51], v[16:19], v[44:47]
	s_cbranch_vccnz .LBB0_981
	v_add_u32_e32 v3, 0xfffffde1, v2
	v_cmp_lt_i32_e32 vcc, -1, v3
	v_add_u32_e32 v3, 0xfffffdd1, v2
	s_nop 3
	v_cndmask_b32_e32 v44, v194, v44, vcc
	v_cmp_lt_i32_e32 vcc, -1, v3
	v_add_u32_e32 v3, 0xfffffdc1, v2
	s_nop 0
	v_cndmask_b32_e32 v45, v194, v45, vcc
	v_cmp_lt_i32_e32 vcc, -1, v3
	v_add_u32_e32 v3, 0xfffffdb1, v2
	s_nop 0
	v_cndmask_b32_e32 v46, v194, v46, vcc
	v_cmp_lt_i32_e32 vcc, -1, v3
	s_nop 1
	v_cndmask_b32_e32 v47, v194, v47, vcc
.LBB0_981:
	ds_read_b128 v[48:51], v97 offset:6912
	v_add_u32_e32 v3, 0x300, v1
	v_cvt_f32_i32_e32 v3, v3
	s_and_b64 vcc, exec, s[16:17]
	v_mul_f32_e32 v52, v160, v3
	v_fma_f32 v54, v160, s90, v52
	v_fma_f32 v55, v161, s91, v52
	v_fma_f32 v53, v165, s59, v52
	v_fma_f32 v52, v164, s58, v52
	s_waitcnt lgkmcnt(0)
	s_nop 0
	v_mfma_f32_16x16x32_bf16 v[48:51], v[48:51], v[12:15], v[52:55]
	s_nop 2
	ds_read_b128 v[52:55], v97 offset:6976
	s_waitcnt lgkmcnt(0)
	v_mfma_f32_16x16x32_bf16 v[48:51], v[52:55], v[16:19], v[48:51]
	s_cbranch_vccnz .LBB0_983
	v_add_u32_e32 v3, 0xfffffce1, v2
	v_cmp_lt_i32_e32 vcc, -1, v3
	v_add_u32_e32 v3, 0xfffffcd1, v2
	s_nop 3
	v_cndmask_b32_e32 v48, v194, v48, vcc
	v_cmp_lt_i32_e32 vcc, -1, v3
	v_add_u32_e32 v3, 0xfffffcc1, v2
	s_nop 0
	v_cndmask_b32_e32 v49, v194, v49, vcc
	v_cmp_lt_i32_e32 vcc, -1, v3
	v_add_u32_e32 v3, 0xfffffcb1, v2
	s_nop 0
	v_cndmask_b32_e32 v50, v194, v50, vcc
	v_cmp_lt_i32_e32 vcc, -1, v3
	s_nop 1
	v_cndmask_b32_e32 v51, v194, v51, vcc
; #define LAS __attribute__((address_space(3)))
; #define MFMA16(a, b, c) __builtin_amdgcn_mfma_f32_16x16x32_bf16(a, b, c, 0, 0, 0)
; __device__ __forceinline__ void nsa_phase(LAS unsigned char* lds, const Args& a, const bf16_t* z, const bf16_t* KC, const bf16_t* VCT, const bf16_t* VST, const bf16_t* VWT, bf16_t* A2, int ldo, bool merged) {
;     ...
;             for (int tl = 0; tl < 4; ++tl) {
;                 if (tl <= tlmax) {
; #pragma unroll
;                     for (int s = 0; s < 4; ++s) {
;                         const LAS unsigned char* kp = lds + kcl_off + (tl * 64 + s * 16) * 144;
;                         const bf16x8 k0 = *(const LAS bf16x8*)kp, k1 = *(const LAS bf16x8*)(kp + 64);
;                         const float cb = slope * (float)((tl * 1024 + s * 256 + 64 * g4 + 31) - tq[qs]);
;                         f32x4 zz;
; #pragma unroll
;                         for (int i = 0; i < 4; ++i) zz[i] = fmaf(slope, 16.f * (float)i, cb);
;                         zz = MFMA16(k0, Qf[qs][0], zz);
;                         zz = MFMA16(k1, Qf[qs][1], zz);
;                         if (!((64 * (tl + 1) - 1) <= (4 * qt - 2))) {
; #pragma unroll
;                             for (int i = 0; i < 4; ++i) {
;                                 const int dist = (tq[qs] - 31 - 64 * g4) - (tl * 1024 + s * 256 + 16 * i);
;                                 const bool ok = (dist >= 0) && !(tl == 3 && s == 3 && i == 3 && g4 == 3);
;                                 zz[i] = ok ? zz[i] : -1e30f;
;                             }
;                         }
; #pragma unroll
;                         for (int i = 0; i < 4; ++i) mx = fmaxf(mx, zz[i]);
;                         sc[tl][s] = zz;
;                         __builtin_amdgcn_sched_barrier(0);
;                     }
;                 } else {
; #pragma unroll
;                     for (int s = 0; s < 4; ++s) sc[tl][s] = (f32x4){-1e30f, -1e30f, -1e30f, -1e30f};
;                 }
;             }
;             mx = fmaxf(mx, __shfl_xor(mx, 16)); mx = fmaxf(mx, __shfl_xor(mx, 32));
.LBB0_983:
	v_mov_b32_e32 v55, 0xf149f2ca
	v_max3_f32 v3, v36, v55, v37
	v_max3_f32 v3, v3, v38, v39
	v_max3_f32 v3, v3, v40, v41
	v_max3_f32 v3, v3, v42, v43
	v_max3_f32 v3, v3, v44, v45
	v_max3_f32 v3, v3, v46, v47
	v_max3_f32 v3, v3, v48, v49
	v_max3_f32 v3, v3, v50, v51
	s_and_b64 vcc, exec, s[10:11]
	s_cbranch_vccnz .LBB0_1000
	ds_read_b128 v[52:55], v97 offset:9216
	v_add_u32_e32 v56, 0x400, v1
	v_cvt_f32_i32_e32 v60, v56
	ds_read_b128 v[56:59], v97 offset:9280
	v_mov_b32_e32 v161, v160
	s_cmp_lt_u32 s63, 33
	v_mul_f32_e32 v60, v160, v60
	v_fma_f32 v62, v160, s90, v60
	v_fma_f32 v63, v161, s91, v60
	v_fma_f32 v61, v165, s59, v60
	v_fma_f32 v60, v164, s58, v60
	s_cselect_b64 s[16:17], -1, 0
	s_cmp_gt_u32 s63, 32
	s_waitcnt lgkmcnt(1)
	v_mfma_f32_16x16x32_bf16 v[52:55], v[52:55], v[12:15], v[60:63]
	s_waitcnt lgkmcnt(0)
	v_mfma_f32_16x16x32_bf16 v[52:55], v[56:59], v[16:19], v[52:55]
	s_cbranch_scc1 .LBB0_986
	v_add_u32_e32 v56, 0xfffffbe1, v2
	v_cmp_lt_i32_e32 vcc, -1, v56
	v_add_u32_e32 v56, 0xfffffbd1, v2
	s_nop 3
	v_cndmask_b32_e32 v52, v194, v52, vcc
	v_cmp_lt_i32_e32 vcc, -1, v56
	v_add_u32_e32 v56, 0xfffffbc1, v2
	s_nop 0
	v_cndmask_b32_e32 v53, v194, v53, vcc
	v_cmp_lt_i32_e32 vcc, -1, v56
	v_add_u32_e32 v56, 0xfffffbb1, v2
	s_nop 0
	v_cndmask_b32_e32 v54, v194, v54, vcc
	v_cmp_lt_i32_e32 vcc, -1, v56
	s_nop 1
	v_cndmask_b32_e32 v55, v194, v55, vcc
.LBB0_986:
	ds_read_b128 v[56:59], v97 offset:11520
	v_add_u32_e32 v60, 0x500, v1
	v_cvt_f32_i32_e32 v64, v60
	ds_read_b128 v[60:63], v97 offset:11584
	s_andn2_b64 vcc, exec, s[16:17]
	v_mul_f32_e32 v64, v160, v64
	v_fma_f32 v66, v160, s90, v64
	v_fma_f32 v67, v161, s91, v64
	v_fma_f32 v65, v165, s59, v64
	v_fma_f32 v64, v164, s58, v64
	s_waitcnt lgkmcnt(1)
	s_nop 0
	v_mfma_f32_16x16x32_bf16 v[56:59], v[56:59], v[12:15], v[64:67]
	s_waitcnt lgkmcnt(0)
	v_mfma_f32_16x16x32_bf16 v[56:59], v[60:63], v[16:19], v[56:59]
	s_nop 0
	v_cndmask_b32_e64 v64, 0, 1, s[16:17]
	v_cmp_ne_u32_e64 s[0:1], 1, v64
	s_cbranch_vccnz .LBB0_988
	v_add_u32_e32 v60, 0xfffffae1, v2
	v_cmp_lt_i32_e32 vcc, -1, v60
	v_add_u32_e32 v60, 0xfffffad1, v2
	s_nop 0
	v_cndmask_b32_e32 v56, v194, v56, vcc
	v_cmp_lt_i32_e32 vcc, -1, v60
	v_add_u32_e32 v60, 0xfffffac1, v2
	s_nop 0
	v_cndmask_b32_e32 v57, v194, v57, vcc
	v_cmp_lt_i32_e32 vcc, -1, v60
	v_add_u32_e32 v60, 0xfffffab1, v2
	s_nop 0
	v_cndmask_b32_e32 v58, v194, v58, vcc
	v_cmp_lt_i32_e32 vcc, -1, v60
	s_nop 1
	v_cndmask_b32_e32 v59, v194, v59, vcc
.LBB0_988:
	ds_read_b128 v[60:63], v97 offset:13824
	v_add_u32_e32 v64, 0x600, v1
	v_cvt_f32_i32_e32 v64, v64
	v_mov_b32_e32 v161, v160
	s_and_b64 vcc, exec, s[0:1]
	v_mul_f32_e32 v64, v160, v64
	v_fma_f32 v66, v160, s90, v64
	v_fma_f32 v67, v161, s91, v64
	v_fma_f32 v65, v165, s59, v64
	v_fma_f32 v64, v164, s58, v64
	s_waitcnt lgkmcnt(0)
	s_nop 0
	v_mfma_f32_16x16x32_bf16 v[60:63], v[60:63], v[12:15], v[64:67]
	s_nop 2
	ds_read_b128 v[64:67], v97 offset:13888
	s_waitcnt lgkmcnt(0)
	v_mfma_f32_16x16x32_bf16 v[60:63], v[64:67], v[16:19], v[60:63]
	s_cbranch_vccnz .LBB0_990
	v_add_u32_e32 v64, 0xfffff9e1, v2
	v_cmp_lt_i32_e32 vcc, -1, v64
	v_add_u32_e32 v64, 0xfffff9d1, v2
	s_nop 3
	v_cndmask_b32_e32 v60, v194, v60, vcc
	v_cmp_lt_i32_e32 vcc, -1, v64
	v_add_u32_e32 v64, 0xfffff9c1, v2
	s_nop 0
	v_cndmask_b32_e32 v61, v194, v61, vcc
	v_cmp_lt_i32_e32 vcc, -1, v64
	v_add_u32_e32 v64, 0xfffff9b1, v2
	s_nop 0
	v_cndmask_b32_e32 v62, v194, v62, vcc
	v_cmp_lt_i32_e32 vcc, -1, v64
	s_nop 1
	v_cndmask_b32_e32 v63, v194, v63, vcc
.LBB0_990:
	ds_read_b128 v[64:67], v97 offset:16128
	v_add_u32_e32 v68, 0x700, v1
	v_cvt_f32_i32_e32 v68, v68
	s_and_b64 vcc, exec, s[0:1]
	v_mul_f32_e32 v68, v160, v68
	v_fma_f32 v70, v160, s90, v68
	v_fma_f32 v71, v161, s91, v68
	v_fma_f32 v69, v165, s59, v68
	v_fma_f32 v68, v164, s58, v68
	s_waitcnt lgkmcnt(0)
	s_nop 0
	v_mfma_f32_16x16x32_bf16 v[64:67], v[64:67], v[12:15], v[68:71]
	s_nop 2
	ds_read_b128 v[68:71], v97 offset:16192
	s_waitcnt lgkmcnt(0)
	v_mfma_f32_16x16x32_bf16 v[64:67], v[68:71], v[16:19], v[64:67]
	s_cbranch_vccnz .LBB0_992
	v_add_u32_e32 v68, 0xfffff8e1, v2
	v_cmp_lt_i32_e32 vcc, -1, v68
	v_add_u32_e32 v68, 0xfffff8d1, v2
	s_nop 3
	v_cndmask_b32_e32 v64, v194, v64, vcc
	v_cmp_lt_i32_e32 vcc, -1, v68
	v_add_u32_e32 v68, 0xfffff8c1, v2
	s_nop 0
	v_cndmask_b32_e32 v65, v194, v65, vcc
	v_cmp_lt_i32_e32 vcc, -1, v68
	v_add_u32_e32 v68, 0xfffff8b1, v2
	s_nop 0
	v_cndmask_b32_e32 v66, v194, v66, vcc
	v_cmp_lt_i32_e32 vcc, -1, v68
	s_nop 1
	v_cndmask_b32_e32 v67, v194, v67, vcc

; #define LAS __attribute__((address_space(3)))
; #define MFMA16(a, b, c) __builtin_amdgcn_mfma_f32_16x16x32_bf16(a, b, c, 0, 0, 0)
; __device__ __forceinline__ void nsa_phase(LAS unsigned char* lds, const Args& a, const bf16_t* z, const bf16_t* KC, const bf16_t* VCT, const bf16_t* VST, const bf16_t* VWT, bf16_t* A2, int ldo, bool merged) {
;     ...
;             for (int tl = 0; tl < 4; ++tl) {
;                 if (tl <= tlmax) {
; #pragma unroll
;                     for (int s = 0; s < 4; ++s) {
;                         const LAS unsigned char* kp = lds + kcl_off + (tl * 64 + s * 16) * 144;
;                         const bf16x8 k0 = *(const LAS bf16x8*)kp, k1 = *(const LAS bf16x8*)(kp + 64);
;                         const float cb = slope * (float)((tl * 1024 + s * 256 + 64 * g4 + 31) - tq[qs]);
;                         f32x4 zz;
; #pragma unroll
;                         for (int i = 0; i < 4; ++i) zz[i] = fmaf(slope, 16.f * (float)i, cb);
;                         zz = MFMA16(k0, Qf[qs][0], zz);
;                         zz = MFMA16(k1, Qf[qs][1], zz);
;                         if (!((64 * (tl + 1) - 1) <= (4 * qt - 2))) {
; #pragma unroll
;                             for (int i = 0; i < 4; ++i) {
;                                 const int dist = (tq[qs] - 31 - 64 * g4) - (tl * 1024 + s * 256 + 16 * i);
;                                 const bool ok = (dist >= 0) && !(tl == 3 && s == 3 && i == 3 && g4 == 3);
;                                 zz[i] = ok ? zz[i] : -1e30f;
;                             }
;                         }
; #pragma unroll
;                         for (int i = 0; i < 4; ++i) mx = fmaxf(mx, zz[i]);
;                         sc[tl][s] = zz;
;                         __builtin_amdgcn_sched_barrier(0);
;                     }
.LBB0_1001:
	ds_read_b128 v[68:71], v97 offset:18432
	v_add_u32_e32 v72, 0x800, v1
	v_cvt_f32_i32_e32 v76, v72
	ds_read_b128 v[72:75], v97 offset:18496
	v_mov_b32_e32 v161, v160
	s_cmp_lt_u32 s63, 49
	v_mul_f32_e32 v76, v160, v76
	v_fma_f32 v78, v160, s90, v76
	v_fma_f32 v79, v161, s91, v76
	v_fma_f32 v77, v165, s59, v76
	v_fma_f32 v76, v164, s58, v76
	s_cselect_b64 s[16:17], -1, 0
	s_cmp_gt_u32 s63, 48
	s_waitcnt lgkmcnt(1)
	v_mfma_f32_16x16x32_bf16 v[68:71], v[68:71], v[12:15], v[76:79]
	s_waitcnt lgkmcnt(0)
	v_mfma_f32_16x16x32_bf16 v[68:71], v[72:75], v[16:19], v[68:71]
	s_cbranch_scc1 .LBB0_1003
	v_add_u32_e32 v72, 0xfffff7e1, v2
	v_cmp_lt_i32_e32 vcc, -1, v72
	v_add_u32_e32 v72, 0xfffff7d1, v2
	s_nop 3
	v_cndmask_b32_e32 v68, v194, v68, vcc
	v_cmp_lt_i32_e32 vcc, -1, v72
	v_add_u32_e32 v72, 0xfffff7c1, v2
	s_nop 0
	v_cndmask_b32_e32 v69, v194, v69, vcc
	v_cmp_lt_i32_e32 vcc, -1, v72
	v_add_u32_e32 v72, 0xfffff7b1, v2
	s_nop 0
	v_cndmask_b32_e32 v70, v194, v70, vcc
	v_cmp_lt_i32_e32 vcc, -1, v72
	s_nop 1
	v_cndmask_b32_e32 v71, v194, v71, vcc
.LBB0_1003:
	ds_read_b128 v[72:75], v97 offset:20736
	v_add_u32_e32 v76, 0x900, v1
	v_cvt_f32_i32_e32 v80, v76
	ds_read_b128 v[76:79], v97 offset:20800
	s_andn2_b64 vcc, exec, s[16:17]
	v_mul_f32_e32 v80, v160, v80
	v_fma_f32 v82, v160, s90, v80
	v_fma_f32 v83, v161, s91, v80
	v_fma_f32 v81, v165, s59, v80
	v_fma_f32 v80, v164, s58, v80
	s_waitcnt lgkmcnt(1)
	s_nop 0
	v_mfma_f32_16x16x32_bf16 v[72:75], v[72:75], v[12:15], v[80:83]
	s_waitcnt lgkmcnt(0)
	v_mfma_f32_16x16x32_bf16 v[72:75], v[76:79], v[16:19], v[72:75]
	s_nop 0
	v_cndmask_b32_e64 v80, 0, 1, s[16:17]
	v_cmp_ne_u32_e64 s[0:1], 1, v80
	s_cbranch_vccnz .LBB0_1005
	v_add_u32_e32 v76, 0xfffff6e1, v2
	v_cmp_lt_i32_e32 vcc, -1, v76
	v_add_u32_e32 v76, 0xfffff6d1, v2
	s_nop 0
	v_cndmask_b32_e32 v72, v194, v72, vcc
	v_cmp_lt_i32_e32 vcc, -1, v76
	v_add_u32_e32 v76, 0xfffff6c1, v2
	s_nop 0
	v_cndmask_b32_e32 v73, v194, v73, vcc
	v_cmp_lt_i32_e32 vcc, -1, v76
	v_add_u32_e32 v76, 0xfffff6b1, v2
	s_nop 0
	v_cndmask_b32_e32 v74, v194, v74, vcc
	v_cmp_lt_i32_e32 vcc, -1, v76
	s_nop 1
	v_cndmask_b32_e32 v75, v194, v75, vcc
.LBB0_1005:
	ds_read_b128 v[76:79], v97 offset:23040
	v_add_u32_e32 v80, 0xa00, v1
	v_cvt_f32_i32_e32 v80, v80
	v_mov_b32_e32 v161, v160
	s_and_b64 vcc, exec, s[0:1]
	v_mul_f32_e32 v80, v160, v80
	v_fma_f32 v82, v160, s90, v80
	v_fma_f32 v83, v161, s91, v80
	v_fma_f32 v81, v165, s59, v80
	v_fma_f32 v80, v164, s58, v80
	s_waitcnt lgkmcnt(0)
	s_nop 0
	v_mfma_f32_16x16x32_bf16 v[76:79], v[76:79], v[12:15], v[80:83]
	s_nop 2
	ds_read_b128 v[80:83], v97 offset:23104
	s_waitcnt lgkmcnt(0)
	v_mfma_f32_16x16x32_bf16 v[76:79], v[80:83], v[16:19], v[76:79]
	s_cbranch_vccnz .LBB0_1007
	v_add_u32_e32 v80, 0xfffff5e1, v2
	v_cmp_lt_i32_e32 vcc, -1, v80
	v_add_u32_e32 v80, 0xfffff5d1, v2
	s_nop 3
	v_cndmask_b32_e32 v76, v194, v76, vcc
	v_cmp_lt_i32_e32 vcc, -1, v80
	v_add_u32_e32 v80, 0xfffff5c1, v2
	s_nop 0
	v_cndmask_b32_e32 v77, v194, v77, vcc
	v_cmp_lt_i32_e32 vcc, -1, v80
	v_add_u32_e32 v80, 0xfffff5b1, v2
	s_nop 0
	v_cndmask_b32_e32 v78, v194, v78, vcc
	v_cmp_lt_i32_e32 vcc, -1, v80
	s_nop 1
	v_cndmask_b32_e32 v79, v194, v79, vcc
.LBB0_1007:
	ds_read_b128 v[80:83], v97 offset:25344
	v_add_u32_e32 v84, 0xb00, v1
	v_cvt_f32_i32_e32 v84, v84
	s_and_b64 vcc, exec, s[0:1]
	v_mul_f32_e32 v84, v160, v84
	v_fma_f32 v86, v160, s90, v84
	v_fma_f32 v87, v161, s91, v84
	v_fma_f32 v85, v165, s59, v84
	v_fma_f32 v84, v164, s58, v84
	s_waitcnt lgkmcnt(0)
	s_nop 0
	v_mfma_f32_16x16x32_bf16 v[80:83], v[80:83], v[12:15], v[84:87]
	s_nop 2
	ds_read_b128 v[84:87], v97 offset:25408
	s_waitcnt lgkmcnt(0)
	v_mfma_f32_16x16x32_bf16 v[84:87], v[84:87], v[16:19], v[80:83]
	s_cbranch_vccnz .LBB0_1009
	s_nop 1
	v_add_u32_e32 v80, 0xfffff4e1, v2
	v_cmp_lt_i32_e32 vcc, -1, v80
	v_add_u32_e32 v80, 0xfffff4d1, v2
	s_nop 1
	v_cndmask_b32_e32 v84, v194, v84, vcc
	v_cmp_lt_i32_e32 vcc, -1, v80
	v_add_u32_e32 v80, 0xfffff4c1, v2
	s_nop 0
	v_cndmask_b32_e32 v85, v194, v85, vcc
	v_cmp_lt_i32_e32 vcc, -1, v80
	v_add_u32_e32 v80, 0xfffff4b1, v2
	s_nop 0
	v_cndmask_b32_e32 v86, v194, v86, vcc
	v_cmp_lt_i32_e32 vcc, -1, v80
	s_nop 1
	v_cndmask_b32_e32 v87, v194, v87, vcc

; #define LAS __attribute__((address_space(3)))
; #define MFMA16(a, b, c) __builtin_amdgcn_mfma_f32_16x16x32_bf16(a, b, c, 0, 0, 0)
; __device__ __forceinline__ void nsa_phase(LAS unsigned char* lds, const Args& a, const bf16_t* z, const bf16_t* KC, const bf16_t* VCT, const bf16_t* VST, const bf16_t* VWT, bf16_t* A2, int ldo, bool merged) {
;     ...
;             for (int tl = 0; tl < 4; ++tl) {
;                 if (tl <= tlmax) {
; #pragma unroll
;                     for (int s = 0; s < 4; ++s) {
;                         const LAS unsigned char* kp = lds + kcl_off + (tl * 64 + s * 16) * 144;
;                         const bf16x8 k0 = *(const LAS bf16x8*)kp, k1 = *(const LAS bf16x8*)(kp + 64);
;                         const float cb = slope * (float)((tl * 1024 + s * 256 + 64 * g4 + 31) - tq[qs]);
;                         f32x4 zz;
; #pragma unroll
;                         for (int i = 0; i < 4; ++i) zz[i] = fmaf(slope, 16.f * (float)i, cb);
;                         zz = MFMA16(k0, Qf[qs][0], zz);
;                         zz = MFMA16(k1, Qf[qs][1], zz);
;                         if (!((64 * (tl + 1) - 1) <= (4 * qt - 2))) {
; #pragma unroll
;                             for (int i = 0; i < 4; ++i) {
;                                 const int dist = (tq[qs] - 31 - 64 * g4) - (tl * 1024 + s * 256 + 16 * i);
;                                 const bool ok = (dist >= 0) && !(tl == 3 && s == 3 && i == 3 && g4 == 3);
;                                 zz[i] = ok ? zz[i] : -1e30f;
;                             }
;                         }
; #pragma unroll
;                         for (int i = 0; i < 4; ++i) mx = fmaxf(mx, zz[i]);
;                         sc[tl][s] = zz;
;                         __builtin_amdgcn_sched_barrier(0);
;                     }
;                 } else {
; #pragma unroll
;                     for (int s = 0; s < 4; ++s) sc[tl][s] = (f32x4){-1e30f, -1e30f, -1e30f, -1e30f};
;                 }
;             }
;             mx = fmaxf(mx, __shfl_xor(mx, 16)); mx = fmaxf(mx, __shfl_xor(mx, 32));
.LBB0_1010:
	ds_read_b128 v[80:83], v97 offset:27648
	v_add_u32_e32 v88, 0xc00, v1
	v_cvt_f32_i32_e32 v92, v88
	ds_read_b128 v[88:91], v97 offset:27712
	v_mov_b32_e32 v161, v160
	v_mul_f32_e32 v92, v160, v92
	v_fma_f32 v94, v160, s90, v92
	v_fma_f32 v95, v161, s91, v92
	v_fma_f32 v93, v165, s59, v92
	v_fma_f32 v92, v164, s58, v92
	s_waitcnt lgkmcnt(1)
	s_nop 0
	v_mfma_f32_16x16x32_bf16 v[80:83], v[80:83], v[12:15], v[92:95]
	s_waitcnt lgkmcnt(0)
	v_mfma_f32_16x16x32_bf16 v[80:83], v[88:91], v[16:19], v[80:83]
	s_nop 0
	v_add_u32_e32 v92, 0xfffff3e1, v2
	v_add_u32_e32 v93, 0xfffff3d1, v2
	v_cmp_lt_i32_e32 vcc, -1, v92
	v_add_u32_e32 v94, 0xfffff3c1, v2
	s_nop 2
	v_cndmask_b32_e32 v119, v194, v80, vcc
	v_cmp_lt_i32_e32 vcc, -1, v93
	v_add_u32_e32 v80, 0xfffff3b1, v2
	s_nop 0
	v_cndmask_b32_e32 v120, v194, v81, vcc
	v_cmp_lt_i32_e32 vcc, -1, v94
	v_max3_f32 v3, v3, v119, v120
	s_nop 0
	v_cndmask_b32_e32 v121, v194, v82, vcc
	v_cmp_lt_i32_e32 vcc, -1, v80
	s_nop 1
	v_cndmask_b32_e32 v122, v194, v83, vcc
	v_max3_f32 v3, v3, v121, v122
	ds_read_b128 v[80:83], v97 offset:29952
	v_add_u32_e32 v88, 0xd00, v1
	v_cvt_f32_i32_e32 v92, v88
	ds_read_b128 v[88:91], v97 offset:30016
	v_mul_f32_e32 v92, v160, v92
	v_fma_f32 v94, v160, s90, v92
	v_fma_f32 v95, v161, s91, v92
	v_fma_f32 v93, v165, s59, v92
	v_fma_f32 v92, v164, s58, v92
	s_waitcnt lgkmcnt(1)
	s_nop 0
	v_mfma_f32_16x16x32_bf16 v[80:83], v[80:83], v[12:15], v[92:95]
	s_waitcnt lgkmcnt(0)
	v_mfma_f32_16x16x32_bf16 v[80:83], v[88:91], v[16:19], v[80:83]
	s_nop 0
	v_add_u32_e32 v92, 0xfffff2e1, v2
	v_add_u32_e32 v93, 0xfffff2d1, v2
	v_cmp_lt_i32_e32 vcc, -1, v92
	v_add_u32_e32 v94, 0xfffff2c1, v2
	s_nop 2
	v_cndmask_b32_e32 v123, v194, v80, vcc
	v_cmp_lt_i32_e32 vcc, -1, v93
	v_add_u32_e32 v80, 0xfffff2b1, v2
	s_nop 0
	v_cndmask_b32_e32 v124, v194, v81, vcc
	v_cmp_lt_i32_e32 vcc, -1, v94
	v_max3_f32 v3, v3, v123, v124
	s_nop 0
	v_cndmask_b32_e32 v125, v194, v82, vcc
	v_cmp_lt_i32_e32 vcc, -1, v80
	s_nop 1
	v_cndmask_b32_e32 v126, v194, v83, vcc
	v_max3_f32 v3, v3, v125, v126
	ds_read_b128 v[80:83], v97 offset:32256
	v_add_u32_e32 v88, 0xe00, v1
	v_cvt_f32_i32_e32 v92, v88
	ds_read_b128 v[88:91], v97 offset:32320
	v_mul_f32_e32 v92, v160, v92
	v_fma_f32 v94, v160, s90, v92
	v_fma_f32 v95, v161, s91, v92
	v_fma_f32 v93, v165, s59, v92
	v_fma_f32 v92, v164, s58, v92
	s_waitcnt lgkmcnt(1)
	s_nop 0
	v_mfma_f32_16x16x32_bf16 v[80:83], v[80:83], v[12:15], v[92:95]
	s_waitcnt lgkmcnt(0)
	v_mfma_f32_16x16x32_bf16 v[80:83], v[88:91], v[16:19], v[80:83]
	s_nop 0
	v_add_u32_e32 v92, 0xfffff1e1, v2
	v_add_u32_e32 v93, 0xfffff1d1, v2
	v_cmp_lt_i32_e32 vcc, -1, v92
	v_add_u32_e32 v94, 0xfffff1c1, v2
	s_nop 2
	v_cndmask_b32_e32 v127, v194, v80, vcc
	v_cmp_lt_i32_e32 vcc, -1, v93
	v_add_u32_e32 v80, 0xfffff1b1, v2
	s_nop 0
	v_cndmask_b32_e32 v128, v194, v81, vcc
	v_cmp_lt_i32_e32 vcc, -1, v94
	v_max3_f32 v3, v3, v127, v128
	s_nop 0
	v_cndmask_b32_e32 v129, v194, v82, vcc
	v_cmp_lt_i32_e32 vcc, -1, v80
	s_nop 1
	v_cndmask_b32_e32 v137, v194, v83, vcc
	v_max3_f32 v3, v3, v129, v137
	ds_read_b128 v[80:83], v97 offset:34560
	ds_read_b128 v[88:91], v97 offset:34624
	v_add_u32_e32 v1, 0xf00, v1
	v_cvt_f32_i32_e32 v1, v1
	v_mul_f32_e32 v92, v160, v1
	v_fma_f32 v94, v160, s90, v92
	v_fma_f32 v95, v161, s91, v92
	v_fma_f32 v93, v165, s59, v92
	v_fma_f32 v92, v164, s58, v92
	v_add_u32_e32 v1, 0xfffff0e1, v2
	v_cmp_lt_i32_e32 vcc, -1, v1
	s_waitcnt lgkmcnt(1)
	v_mfma_f32_16x16x32_bf16 v[80:83], v[80:83], v[12:15], v[92:95]
	v_add_u32_e32 v1, 0xfffff0b1, v2
	s_waitcnt lgkmcnt(0)
	v_mfma_f32_16x16x32_bf16 v[80:83], v[88:91], v[16:19], v[80:83]
	v_add_u32_e32 v92, 0xfffff0d1, v2
	v_add_u32_e32 v93, 0xfffff0c1, v2
	s_nop 5
	v_cndmask_b32_e32 v140, v194, v80, vcc
	v_cmp_lt_i32_e32 vcc, -1, v92
	s_nop 1
	v_cndmask_b32_e32 v141, v194, v81, vcc
	v_cmp_lt_i32_e32 vcc, -1, v93
	s_nop 1
	v_cndmask_b32_e32 v142, v194, v82, vcc
	v_cmp_lt_i32_e32 vcc, -1, v1
	s_and_b64 vcc, vcc, s[14:15]
	v_max3_f32 v1, v3, v140, v141
	v_cndmask_b32_e32 v143, v194, v83, vcc
	v_max3_f32 v3, v1, v142, v143

; #define LAS __attribute__((address_space(3)))
; __device__ __forceinline__ void nsa_phase(LAS unsigned char* lds, const Args& a, const bf16_t* z, const bf16_t* KC, const bf16_t* VCT, const bf16_t* VST, const bf16_t* VWT, bf16_t* A2, int ldo, bool merged) {
;     ...
;             ps += __shfl_xor(ps, 16); ps += __shfl_xor(ps, 32);
;             const float inv = ps > 0.f ? 1.f / ps : 0.f;
;             unsigned imp_off = (unsigned)((hr * 64 + qh * 32 + qs * 16 + l15) * 65 + g4) * 4u; asm volatile("" : "+v"(imp_off));
;             LAS float* impw = (LAS float*)(lds + NS_IMP + imp_off);
;             float prev3 = 0.f;
; #pragma unroll
;             for (int tl = 0; tl < 4; ++tl) {
;                 if (tl <= tlmax) {
; #pragma unroll
;                     for (int s = 0; s < 4; ++s) {
;                         f32x4 p = sc[tl][s] * inv; sc[tl][s] = p;
;                         const float from_same = __shfl(p[3], (lane + 48) & 63);
;                         const float from_prev = __shfl(prev3, (lane + 48) & 63);
;                         const float p3m = (g4 > 0) ? from_same : from_prev;
;                         impw[tl * 16 + s * 4] = p3m + 2.f * (p[0] + p[1] + p[2]) + p[3];
;                         prev3 = p[3];
;                     }
;                 } else {
; #pragma unroll
;                     for (int s = 0; s < 4; ++s) {
;                         const float from_prev = __shfl(prev3, (lane + 48) & 63);
;                         impw[tl * 16 + s * 4] = (g4 > 0) ? 0.f : from_prev;
;                         prev3 = 0.f;
;                     }
;                 }
;             }
.LBB0_1018:
	ds_bpermute_b32 v1, v201, v145
	v_add_u32_e32 v3, v136, v118
	v_lshl_add_u32 v68, v3, 2, v195
	s_waitcnt lgkmcnt(0)
	v_add_f32_e32 v1, v145, v1
	ds_bpermute_b32 v2, v202, v1
	v_add_u32_e32 v3, 0, v68
	v_add_u32_e32 v70, 0x11400, v3
	s_waitcnt lgkmcnt(0)
	v_add_f32_e32 v1, v1, v2
	v_div_scale_f32 v2, s[0:1], v1, v1, 1.0
	v_rcp_f32_e32 v69, v2
	v_div_scale_f32 v3, vcc, 1.0, v1, 1.0
	s_mov_b64 s[0:1], -1
	v_fma_f32 v71, -v2, v69, 1.0
	v_fmac_f32_e32 v69, v71, v69
	v_mul_f32_e32 v71, v3, v69
	v_fma_f32 v72, -v2, v71, v3
	v_fmac_f32_e32 v71, v72, v69
	v_fma_f32 v2, -v2, v71, v3
	v_div_fmas_f32 v2, v2, v69, v71
	v_div_fixup_f32 v2, v2, v1, 1.0
	v_cmp_lt_f32_e32 vcc, 0, v1
	s_nop 1
	v_cndmask_b32_e32 v128, 0, v2, vcc
	v_mov_b32_e32 v129, v128
	v_pk_mul_f32 v[116:117], v[116:117], v[128:129] op_sel_hi:[1,0]
	ds_bpermute_b32 v1, v193, v117
	v_pk_mul_f32 v[120:121], v[110:111], v[128:129] op_sel_hi:[1,0]
	ds_bpermute_b32 v69, v193, v121
	v_pk_mul_f32 v[114:115], v[114:115], v[128:129] op_sel_hi:[1,0]
	v_pk_mul_f32 v[126:127], v[108:109], v[128:129] op_sel_hi:[1,0]
	v_add_f32_e32 v2, v114, v115
	v_add_f32_e32 v2, v116, v2
	s_waitcnt lgkmcnt(1)
	v_cndmask_b32_e64 v3, 0, v1, s[12:13]
	v_fmac_f32_e32 v3, 2.0, v2
	v_add_f32_e32 v2, v126, v127
	v_add_f32_e32 v71, v117, v3
	s_waitcnt lgkmcnt(0)
	v_cndmask_b32_e64 v1, v1, v69, s[12:13]
	v_add_f32_e32 v72, v120, v2
	v_pk_mul_f32 v[2:3], v[98:99], v[128:129] op_sel_hi:[1,0]
	ds_bpermute_b32 v73, v193, v3
	v_fmac_f32_e32 v1, 2.0, v72
	v_add_f32_e32 v1, v121, v1
	v_pk_mul_f32 v[122:123], v[90:91], v[128:129] op_sel_hi:[1,0]
	ds_write2_b32 v70, v71, v1 offset1:4
	ds_bpermute_b32 v71, v193, v123
	v_pk_mul_f32 v[118:119], v[96:97], v[128:129] op_sel_hi:[1,0]
	s_waitcnt lgkmcnt(2)
	v_cndmask_b32_e64 v1, v69, v73, s[12:13]
	v_add_f32_e32 v69, v118, v119
	v_add_f32_e32 v69, v2, v69
	v_pk_mul_f32 v[124:125], v[88:89], v[128:129] op_sel_hi:[1,0]
	v_fmac_f32_e32 v1, 2.0, v69
	s_waitcnt lgkmcnt(0)
	v_cndmask_b32_e64 v69, v73, v71, s[12:13]
	v_add_f32_e32 v71, v124, v125
	v_add_f32_e32 v71, v122, v71
	v_fmac_f32_e32 v69, 2.0, v71
	v_add_f32_e32 v1, v3, v1
	v_add_f32_e32 v69, v123, v69
	ds_write2_b32 v70, v1, v69 offset0:8 offset1:12
	s_and_b64 vcc, exec, s[10:11]
	v_add_u32_e32 v1, s33, v68
	s_cbranch_vccnz .LBB0_1020
	v_mov_b32_e32 v68, v128
	v_mov_b32_e32 v69, v128
	v_pk_mul_f32 v[90:91], v[82:83], v[68:69]
	ds_bpermute_b32 v70, v193, v123
	ds_bpermute_b32 v76, v193, v91
	v_pk_mul_f32 v[98:99], v[94:95], v[68:69]
	v_pk_mul_f32 v[74:75], v[102:103], v[68:69]
	v_pk_mul_f32 v[88:89], v[80:81], v[128:129]
	ds_bpermute_b32 v77, v193, v99
	ds_bpermute_b32 v84, v193, v75
	v_add_f32_e32 v71, v88, v89
	s_waitcnt lgkmcnt(2)
	v_cndmask_b32_e64 v70, v70, v76, s[12:13]
	v_add_f32_e32 v71, v90, v71
	v_fmac_f32_e32 v70, 2.0, v71
	v_add_f32_e32 v70, v91, v70
	v_pk_mul_f32 v[96:97], v[92:93], v[128:129]
	v_pk_mul_f32 v[72:73], v[100:101], v[128:129]
	ds_write_b32 v1, v70 offset:64
	s_waitcnt lgkmcnt(1)
	v_cndmask_b32_e64 v71, v77, v84, s[12:13]
	v_cndmask_b32_e64 v70, v76, v77, s[12:13]
	v_mov_b32_e32 v76, v96
	v_mov_b32_e32 v77, v72
	v_mov_b32_e32 v78, v97
	v_mov_b32_e32 v79, v73
	v_pk_add_f32 v[76:77], v[76:77], v[78:79]
	v_mov_b32_e32 v78, v98
	v_mov_b32_e32 v79, v74
	v_pk_add_f32 v[76:77], v[78:79], v[76:77]
	v_pk_mul_f32 v[110:111], v[106:107], v[68:69]
	v_fma_f32 v70, v76, 2.0, v70
	v_fma_f32 v71, v77, 2.0, v71
	ds_bpermute_b32 v76, v193, v111
	v_mov_b32_e32 v68, v99
	v_mov_b32_e32 v69, v75
	v_pk_mul_f32 v[108:109], v[104:105], v[128:129]
	v_pk_add_f32 v[68:69], v[68:69], v[70:71]
	v_add_f32_e32 v71, v108, v109
	s_waitcnt lgkmcnt(0)
	v_cndmask_b32_e64 v70, v84, v76, s[12:13]
	v_add_f32_e32 v71, v110, v71
	v_fmac_f32_e32 v70, 2.0, v71
	v_mov_b64_e32 v[84:85], v[108:109]
	v_add_f32_e32 v70, v111, v70
	s_mov_b64 s[0:1], 0
	v_mov_b64_e32 v[86:87], v[110:111]

; __device__ __forceinline__ void nsa_phase(LAS unsigned char* lds, const Args& a, const bf16_t* z, const bf16_t* KC, const bf16_t* VCT, const bf16_t* VST, const bf16_t* VWT, bf16_t* A2, int ldo, bool merged) {
;     ...
;             for (int tl = 0; tl < 4; ++tl) {
;                 if (tl <= tlmax) {
; #pragma unroll
;                     for (int s = 0; s < 4; ++s) {
;                         f32x4 p = sc[tl][s] * inv; sc[tl][s] = p;
;                         const float from_same = __shfl(p[3], (lane + 48) & 63);
;                         const float from_prev = __shfl(prev3, (lane + 48) & 63);
;                         const float p3m = (g4 > 0) ? from_same : from_prev;
;                         impw[tl * 16 + s * 4] = p3m + 2.f * (p[0] + p[1] + p[2]) + p[3];
;                         prev3 = p[3];
;                     }
;                 } else {
; #pragma unroll
;                     for (int s = 0; s < 4; ++s) {
;                         const float from_prev = __shfl(prev3, (lane + 48) & 63);
;                         impw[tl * 16 + s * 4] = (g4 > 0) ? 0.f : from_prev;
;                         prev3 = 0.f;
;                     }
;                 }
;             }
.LBB0_1022:
	s_and_b64 vcc, exec, s[8:9]
	s_mov_b64 s[0:1], -1
	ds_write2_b32 v1, v68, v69 offset0:20 offset1:24
	ds_write_b32 v1, v70 offset:112
	s_cbranch_vccnz .LBB0_1024
	v_mov_b32_e32 v76, v128
	v_mov_b32_e32 v77, v128
	v_pk_mul_f32 v[82:83], v[38:39], v[76:77]
	ds_bpermute_b32 v68, v193, v111
	ds_bpermute_b32 v78, v193, v83
	v_pk_mul_f32 v[80:81], v[36:37], v[128:129]
	v_pk_mul_f32 v[94:95], v[42:43], v[76:77]
	v_pk_mul_f32 v[70:71], v[46:47], v[76:77]
	v_add_f32_e32 v69, v80, v81
	ds_bpermute_b32 v100, v193, v95
	ds_bpermute_b32 v106, v193, v71
	s_waitcnt lgkmcnt(2)
	v_cndmask_b32_e64 v68, v68, v78, s[12:13]
	v_add_f32_e32 v69, v82, v69
	v_fmac_f32_e32 v68, 2.0, v69
	v_add_f32_e32 v68, v83, v68
	ds_write_b32 v1, v68 offset:128
	v_pk_mul_f32 v[92:93], v[40:41], v[128:129]
	v_pk_mul_f32 v[68:69], v[44:45], v[128:129]
	s_waitcnt lgkmcnt(1)
	v_cndmask_b32_e64 v79, v100, v106, s[12:13]
	v_cndmask_b32_e64 v78, v78, v100, s[12:13]
	v_mov_b32_e32 v100, v92
	v_mov_b32_e32 v101, v68
	v_mov_b32_e32 v102, v93
	v_mov_b32_e32 v103, v69
	v_pk_add_f32 v[100:101], v[100:101], v[102:103]
	v_mov_b32_e32 v102, v94
	v_mov_b32_e32 v103, v70
	v_pk_add_f32 v[100:101], v[102:103], v[100:101]
	v_pk_mul_f32 v[102:103], v[50:51], v[76:77]
	ds_bpermute_b32 v107, v193, v103
	v_fma_f32 v78, v100, 2.0, v78
	v_fma_f32 v79, v101, 2.0, v79
	v_mov_b32_e32 v76, v95
	v_mov_b32_e32 v77, v71
	v_pk_mul_f32 v[100:101], v[48:49], v[128:129]
	v_pk_add_f32 v[104:105], v[76:77], v[78:79]
	v_add_f32_e32 v77, v100, v101
	s_waitcnt lgkmcnt(0)
	v_cndmask_b32_e64 v76, v106, v107, s[12:13]
	v_add_f32_e32 v77, v102, v77
	v_fmac_f32_e32 v76, 2.0, v77
	v_add_f32_e32 v106, v103, v76
	v_mov_b64_e32 v[76:77], v[100:101]
	s_mov_b64 s[0:1], 0
	v_mov_b64_e32 v[78:79], v[102:103]

; __device__ __forceinline__ void nsa_phase(LAS unsigned char* lds, const Args& a, const bf16_t* z, const bf16_t* KC, const bf16_t* VCT, const bf16_t* VST, const bf16_t* VWT, bf16_t* A2, int ldo, bool merged) {
;     ...
;             for (int tl = 0; tl < 4; ++tl) {
;                 if (tl <= tlmax) {
; #pragma unroll
;                     for (int s = 0; s < 4; ++s) {
;                         f32x4 p = sc[tl][s] * inv; sc[tl][s] = p;
;                         const float from_same = __shfl(p[3], (lane + 48) & 63);
;                         const float from_prev = __shfl(prev3, (lane + 48) & 63);
;                         const float p3m = (g4 > 0) ? from_same : from_prev;
;                         impw[tl * 16 + s * 4] = p3m + 2.f * (p[0] + p[1] + p[2]) + p[3];
;                         prev3 = p[3];
;                     }
;                 } else {
; #pragma unroll
;                     for (int s = 0; s < 4; ++s) {
;                         const float from_prev = __shfl(prev3, (lane + 48) & 63);
;                         impw[tl * 16 + s * 4] = (g4 > 0) ? 0.f : from_prev;
;                         prev3 = 0.f;
;                     }
;                 }
;             }
.LBB0_1028:
	s_andn2_b64 vcc, exec, s[0:1]
	v_mov_b32_e32 v39, 0
	s_cbranch_vccnz .LBB0_1030
	v_mov_b32_e32 v36, v128
	v_mov_b32_e32 v37, v128
	v_pk_mul_f32 v[62:63], v[62:63], v[36:37]
	ds_bpermute_b32 v38, v193, v103
	ds_bpermute_b32 v39, v193, v63
	v_pk_mul_f32 v[66:67], v[66:67], v[36:37]
	v_pk_mul_f32 v[54:55], v[54:55], v[36:37]
	ds_bpermute_b32 v42, v193, v67
	ds_bpermute_b32 v46, v193, v55
	v_pk_mul_f32 v[60:61], v[60:61], v[128:129]
	s_waitcnt lgkmcnt(2)
	v_cndmask_b32_e64 v38, v38, v39, s[12:13]
	v_add_f32_e32 v40, v60, v61
	v_add_f32_e32 v40, v62, v40
	v_pk_mul_f32 v[64:65], v[64:65], v[128:129]
	v_pk_mul_f32 v[52:53], v[52:53], v[128:129]
	v_pk_mul_f32 v[58:59], v[58:59], v[36:37]
	v_fmac_f32_e32 v38, 2.0, v40
	s_waitcnt lgkmcnt(0)
	v_cndmask_b32_e64 v41, v42, v46, s[12:13]
	v_cndmask_b32_e64 v40, v39, v42, s[12:13]
	v_mov_b32_e32 v42, v64
	v_mov_b32_e32 v43, v52
	v_mov_b32_e32 v44, v65
	v_mov_b32_e32 v45, v53
	ds_bpermute_b32 v39, v193, v59
	v_pk_add_f32 v[42:43], v[42:43], v[44:45]
	v_mov_b32_e32 v44, v66
	v_mov_b32_e32 v45, v54
	v_pk_add_f32 v[42:43], v[44:45], v[42:43]
	v_mov_b32_e32 v36, v67
	v_fma_f32 v40, v42, 2.0, v40
	v_fma_f32 v41, v43, 2.0, v41
	v_mov_b32_e32 v37, v55
	v_pk_mul_f32 v[56:57], v[56:57], v[128:129]
	v_pk_add_f32 v[36:37], v[36:37], v[40:41]
	v_add_f32_e32 v40, v56, v57
	s_waitcnt lgkmcnt(0)
	v_cndmask_b32_e64 v39, v46, v39, s[12:13]
	v_add_f32_e32 v40, v58, v40
	v_fmac_f32_e32 v39, 2.0, v40
	v_add_f32_e32 v38, v63, v38
	v_add_f32_e32 v39, v59, v39
	s_branch .LBB0_1031

; #define LAS __attribute__((address_space(3)))
; #define MFMA16(a, b, c) __builtin_amdgcn_mfma_f32_16x16x32_bf16(a, b, c, 0, 0, 0)
; template <int MODE> ...
;     asm volatile("" : "+v"(kt_off), "+v"(vt_off));
;     const LAS unsigned char* KT = lds + kt_off; const LAS unsigned char* VT = lds + vt_off;
;     f32x4 sc[4][2];
;     float cb[2];
; #pragma unroll
;     for (int qs = 0; qs < 2; ++qs) cb[qs] = slope * (float)(key0 + 4 * g4 - tq[qs]) + ((MODE == 1 && !selb[qs]) ? -1e30f : 0.f);
;     __builtin_amdgcn_s_setprio(1);
; #pragma unroll
;     for (int s = 0; s < 4; ++s) {
;         const LAS unsigned char* kp = KT + (s * 16) * 144;
;         const bf16x8 k0 = *(const LAS bf16x8*)kp, k1 = *(const LAS bf16x8*)(kp + 64);
; #pragma unroll
;         for (int qs = 0; qs < 2; ++qs) {
;             f32x4 zz;
; #pragma unroll
;             for (int i = 0; i < 4; ++i) zz[i] = fmaf(slope, (float)(s * 16 + i), cb[qs]);
;             zz = MFMA16(k0, Qf[qs][0], zz);
;             sc[s][qs] = MFMA16(k1, Qf[qs][1], zz);
;         }
;         __builtin_amdgcn_sched_barrier(0);
;     }
;     __builtin_amdgcn_s_setprio(0);
;     if (!full) {
; #pragma unroll
;         for (int qs = 0; qs < 2; ++qs)
; #pragma unroll
;             for (int s = 0; s < 4; ++s)
; #pragma unroll
;                 for (int i = 0; i < 4; ++i) {
;                     const int dist = (tq[qs] - key0 - 4 * g4) - (s * 16 + i);
;                     const bool ok = (MODE == 1) ? (dist >= 0) : (dist >= 0 && dist < 512);
;                     sc[s][qs][i] = ok ? sc[s][qs][i] : -1e30f;
;                 }
.LBB0_1104:
	v_lshrrev_b64 v[92:93], s9, v[124:125]
	v_and_b32_e32 v94, 1, v92
	v_lshrrev_b64 v[92:93], s9, v[128:129]
	s_lshl_b32 s6, s9, 6
	v_mov_b32_e32 v147, v203
	v_mov_b32_e32 v93, v1
	v_add_u32_e32 v148, s6, v141
	v_add_u32_e32 v149, 0, v93
	v_sub_u32_e32 v93, v148, v138
	v_cmp_eq_u32_e32 vcc, 1, v94
	v_sub_u32_e32 v94, v148, v139
	v_cvt_f32_i32_e32 v93, v93
	v_cvt_f32_i32_e32 v94, v94
	v_and_b32_e32 v92, 1, v92
	v_cndmask_b32_e64 v150, v194, 0, vcc
	v_cmp_eq_u32_e32 vcc, 1, v92
	s_cmp_lt_i32 s9, s63
	v_fmac_f32_e32 v150, v160, v93
	v_cndmask_b32_e64 v154, v194, 0, vcc
	v_fmac_f32_e32 v154, v160, v94
	s_nop 0
	ds_read_b128 v[92:95], v149
	v_fma_f32 v96, 0, v160, v150
	v_add_f32_e32 v97, v160, v150
	v_fma_f32 v98, v162, s56, v150
	v_fma_f32 v99, v163, s57, v150
	v_fma_f32 v100, 0, v160, v154
	v_add_f32_e32 v101, v160, v154
	v_fma_f32 v102, v162, s56, v154
	v_fma_f32 v103, v163, s57, v154
	s_waitcnt lgkmcnt(0)
	v_mfma_f32_16x16x32_bf16 v[96:99], v[92:95], v[4:7], v[96:99]
	v_mfma_f32_16x16x32_bf16 v[92:95], v[92:95], v[12:15], v[100:103]
	s_nop 2
	ds_read_b128 v[100:103], v149 offset:64
	s_waitcnt lgkmcnt(0)
	v_mfma_f32_16x16x32_bf16 v[104:107], v[100:103], v[8:11], v[96:99]
	v_mfma_f32_16x16x32_bf16 v[92:95], v[100:103], v[16:19], v[92:95]
	s_nop 1
	ds_read_b128 v[96:99], v149 offset:2304
	v_mov_b32_e32 v161, v160
	v_fma_f32 v100, v164, s88, v150
	v_fma_f32 v101, v165, s89, v150
	v_fma_f32 v102, v160, s20, v150
	v_fma_f32 v103, v161, s21, v150
	v_fma_f32 v108, v164, s88, v154
	v_fma_f32 v109, v165, s89, v154
	v_fma_f32 v110, v160, s20, v154
	v_fma_f32 v111, v161, s21, v154
	s_waitcnt lgkmcnt(0)
	v_mfma_f32_16x16x32_bf16 v[100:103], v[96:99], v[4:7], v[100:103]
	v_mfma_f32_16x16x32_bf16 v[96:99], v[96:99], v[12:15], v[108:111]
	s_nop 2
	ds_read_b128 v[108:111], v149 offset:2368
	s_waitcnt lgkmcnt(0)
	v_mfma_f32_16x16x32_bf16 v[112:115], v[108:111], v[8:11], v[100:103]
	v_mfma_f32_16x16x32_bf16 v[96:99], v[108:111], v[16:19], v[96:99]
	s_nop 1
	ds_read_b128 v[100:103], v149 offset:4608
	ds_read_b128 v[120:123], v149 offset:4672
	v_fma_f32 v110, v160, s54, v150
	v_fma_f32 v111, v161, s55, v150
	v_fma_f32 v108, v164, s80, v150
	v_fma_f32 v109, v165, s81, v150
	v_fma_f32 v118, v160, s54, v154
	v_fma_f32 v119, v161, s55, v154
	v_fma_f32 v116, v164, s80, v154
	v_fma_f32 v117, v165, s81, v154
	s_waitcnt lgkmcnt(1)
	v_mfma_f32_16x16x32_bf16 v[108:111], v[100:103], v[4:7], v[108:111]
	v_mfma_f32_16x16x32_bf16 v[100:103], v[100:103], v[12:15], v[116:119]
	s_waitcnt lgkmcnt(0)
	v_mfma_f32_16x16x32_bf16 v[116:119], v[120:123], v[8:11], v[108:111]
	v_mfma_f32_16x16x32_bf16 v[100:103], v[120:123], v[16:19], v[100:103]
	s_nop 3
	ds_read_b128 v[108:111], v149 offset:6912
	v_fma_f32 v122, v160, s44, v150
	v_fma_f32 v123, v161, s45, v150
	v_fma_f32 v120, v164, s40, v150
	v_fma_f32 v121, v165, s41, v150
	v_fma_f32 v152, v160, s44, v154
	v_fma_f32 v153, v161, s45, v154
	v_fma_f32 v150, v164, s40, v154
	v_fma_f32 v151, v165, s41, v154
	s_waitcnt lgkmcnt(0)
	v_mfma_f32_16x16x32_bf16 v[120:123], v[108:111], v[4:7], v[120:123]
	v_mfma_f32_16x16x32_bf16 v[108:111], v[108:111], v[12:15], v[150:153]
	s_nop 2
	ds_read_b128 v[150:153], v149 offset:6976
	s_waitcnt lgkmcnt(0)
	v_mfma_f32_16x16x32_bf16 v[120:123], v[150:153], v[8:11], v[120:123]
	v_mfma_f32_16x16x32_bf16 v[108:111], v[150:153], v[16:19], v[108:111]
	s_nop 0
	s_cbranch_scc1 .LBB0_1106
	v_sub_u32_e32 v149, v138, v148
	v_cmp_lt_i32_e32 vcc, -1, v149
	v_or_b32_e32 v149, 1, v148
	v_sub_u32_e32 v150, v138, v149
	v_cndmask_b32_e32 v104, v194, v104, vcc
	v_cmp_lt_i32_e32 vcc, -1, v150
	v_or_b32_e32 v150, 2, v148
	v_sub_u32_e32 v151, v138, v150
	v_cndmask_b32_e32 v105, v194, v105, vcc
	v_cmp_lt_i32_e32 vcc, -1, v151
	v_or_b32_e32 v151, 3, v148
	v_sub_u32_e32 v152, v138, v151
	v_cndmask_b32_e32 v106, v194, v106, vcc
	v_cmp_lt_i32_e32 vcc, -1, v152
	v_add_u32_e32 v152, 16, v148
	v_sub_u32_e32 v153, v138, v152
	v_cndmask_b32_e32 v107, v194, v107, vcc
	v_cmp_lt_i32_e32 vcc, -1, v153
	v_add_u32_e32 v153, 17, v148
	v_sub_u32_e32 v154, v138, v153
	v_cndmask_b32_e32 v112, v194, v112, vcc
	v_cmp_lt_i32_e32 vcc, -1, v154
	v_add_u32_e32 v154, 18, v148
	v_sub_u32_e32 v155, v138, v154
	v_cndmask_b32_e32 v113, v194, v113, vcc
	v_cmp_lt_i32_e32 vcc, -1, v155
	v_add_u32_e32 v155, 19, v148
	v_sub_u32_e32 v161, v138, v155
	v_cndmask_b32_e32 v114, v194, v114, vcc
	v_cmp_lt_i32_e32 vcc, -1, v161
	v_add_u32_e32 v161, 32, v148
	v_sub_u32_e32 v176, v138, v161
	v_cndmask_b32_e32 v115, v194, v115, vcc
	v_cmp_lt_i32_e32 vcc, -1, v176
	v_add_u32_e32 v176, 33, v148
	v_sub_u32_e32 v177, v138, v176
	v_cndmask_b32_e32 v116, v194, v116, vcc
	v_cmp_lt_i32_e32 vcc, -1, v177
	v_add_u32_e32 v177, 34, v148
	v_sub_u32_e32 v178, v138, v177
	v_cndmask_b32_e32 v117, v194, v117, vcc
	v_cmp_lt_i32_e32 vcc, -1, v178
	v_add_u32_e32 v178, 35, v148
	v_sub_u32_e32 v179, v138, v178
	v_cndmask_b32_e32 v118, v194, v118, vcc
	v_cmp_lt_i32_e32 vcc, -1, v179
	v_add_u32_e32 v179, 48, v148
	v_sub_u32_e32 v180, v138, v179
	v_cndmask_b32_e32 v119, v194, v119, vcc
	v_cmp_lt_i32_e32 vcc, -1, v180
	v_add_u32_e32 v180, 49, v148
	v_sub_u32_e32 v181, v138, v180
	v_cndmask_b32_e32 v120, v194, v120, vcc
	v_cmp_lt_i32_e32 vcc, -1, v181
	v_add_u32_e32 v181, 50, v148
	v_sub_u32_e32 v182, v138, v181
	v_cndmask_b32_e32 v121, v194, v121, vcc
	v_cmp_lt_i32_e32 vcc, -1, v182
	v_add_u32_e32 v182, 51, v148
	v_sub_u32_e32 v183, v138, v182
	v_cndmask_b32_e32 v122, v194, v122, vcc
	v_cmp_lt_i32_e32 vcc, -1, v183
	v_sub_u32_e32 v148, v139, v148
	s_nop 0
	v_cndmask_b32_e32 v123, v194, v123, vcc
	v_cmp_lt_i32_e32 vcc, -1, v148
	v_sub_u32_e32 v148, v139, v149
	s_nop 0
; template <int MODE> ...
;     ...
;     if (!full) {
; #pragma unroll
;         for (int qs = 0; qs < 2; ++qs)
; #pragma unroll
;             for (int s = 0; s < 4; ++s)
; #pragma unroll
;                 for (int i = 0; i < 4; ++i) {
;                     const int dist = (tq[qs] - key0 - 4 * g4) - (s * 16 + i);
;                     const bool ok = (MODE == 1) ? (dist >= 0) : (dist >= 0 && dist < 512);
;                     sc[s][qs][i] = ok ? sc[s][qs][i] : -1e30f;
;                 }
;     }
; #pragma unroll
;     for (int qs = 0; qs < 2; ++qs) {
;         float mx = -1e30f;
; #pragma unroll
;         for (int s = 0; s < 4; ++s)
; #pragma unroll
;             for (int i = 0; i < 4; ++i) mx = fmaxf(mx, sc[s][qs][i]);
;         mx = fmaxf(mx, __shfl_xor(mx, 16)); mx = fmaxf(mx, __shfl_xor(mx, 32));
;         const float mn = fmaxf(mrun[qs], mx);
;         const float alpha = __builtin_amdgcn_exp2f(mrun[qs] - mn);
;         mrun[qs] = mn;
;         const float mnx = fmaxf(mn, -1e29f);
;         float ps = 0.f;
; #pragma unroll
;         for (int s = 0; s < 4; ++s)
; #pragma unroll
;             for (int i = 0; i < 4; ++i) { const float p = __builtin_amdgcn_exp2f(sc[s][qs][i] - mnx); sc[s][qs][i] = p; ps += p; }
	v_cndmask_b32_e32 v92, v194, v92, vcc
	v_cmp_lt_i32_e32 vcc, -1, v148
	v_sub_u32_e32 v148, v139, v150
	s_nop 0
	v_cndmask_b32_e32 v93, v194, v93, vcc
	v_cmp_lt_i32_e32 vcc, -1, v148
	v_sub_u32_e32 v148, v139, v151
	s_nop 0
	v_cndmask_b32_e32 v94, v194, v94, vcc
	v_cmp_lt_i32_e32 vcc, -1, v148
	v_sub_u32_e32 v148, v139, v152
	s_nop 0
	v_cndmask_b32_e32 v95, v194, v95, vcc
	v_cmp_lt_i32_e32 vcc, -1, v148
	v_sub_u32_e32 v148, v139, v153
	s_nop 0
	v_cndmask_b32_e32 v96, v194, v96, vcc
	v_cmp_lt_i32_e32 vcc, -1, v148
	v_sub_u32_e32 v148, v139, v154
	s_nop 0
	v_cndmask_b32_e32 v97, v194, v97, vcc
	v_cmp_lt_i32_e32 vcc, -1, v148
	v_sub_u32_e32 v148, v139, v155
	s_nop 0
	v_cndmask_b32_e32 v98, v194, v98, vcc
	v_cmp_lt_i32_e32 vcc, -1, v148
	v_sub_u32_e32 v148, v139, v161
	s_nop 0
	v_cndmask_b32_e32 v99, v194, v99, vcc
	v_cmp_lt_i32_e32 vcc, -1, v148
	v_sub_u32_e32 v148, v139, v176
	s_nop 0
	v_cndmask_b32_e32 v100, v194, v100, vcc
	v_cmp_lt_i32_e32 vcc, -1, v148
	v_sub_u32_e32 v148, v139, v177
	s_nop 0
	v_cndmask_b32_e32 v101, v194, v101, vcc
	v_cmp_lt_i32_e32 vcc, -1, v148
	v_sub_u32_e32 v148, v139, v178
	s_nop 0
	v_cndmask_b32_e32 v102, v194, v102, vcc
	v_cmp_lt_i32_e32 vcc, -1, v148
	v_sub_u32_e32 v148, v139, v179
	s_nop 0
	v_cndmask_b32_e32 v103, v194, v103, vcc
	v_cmp_lt_i32_e32 vcc, -1, v148
	v_sub_u32_e32 v148, v139, v180
	s_nop 0
	v_cndmask_b32_e32 v108, v194, v108, vcc
	v_cmp_lt_i32_e32 vcc, -1, v148
	v_sub_u32_e32 v148, v139, v181
	s_nop 0
	v_cndmask_b32_e32 v109, v194, v109, vcc
	v_cmp_lt_i32_e32 vcc, -1, v148
	v_sub_u32_e32 v148, v139, v182
	s_nop 0
	v_cndmask_b32_e32 v110, v194, v110, vcc
	v_cmp_lt_i32_e32 vcc, -1, v148
	s_nop 1
	v_cndmask_b32_e32 v111, v194, v111, vcc
.LBB0_1106:
	v_max3_f32 v148, v104, s92, v105
	v_max3_f32 v148, v148, v106, v107
	v_max3_f32 v148, v148, v112, v113
	v_max3_f32 v148, v148, v114, v115
	v_max3_f32 v148, v148, v116, v117
	v_max3_f32 v148, v148, v118, v119
	v_max3_f32 v148, v148, v120, v121
	v_max3_f32 v148, v148, v122, v123
	ds_bpermute_b32 v149, v201, v148
	v_add_u32_e32 v161, 0, v147
	s_waitcnt lgkmcnt(0)
	v_max_f32_e32 v149, v149, v149
	v_max_f32_e32 v148, v148, v149
	ds_bpermute_b32 v149, v202, v148
	s_waitcnt lgkmcnt(0)
	v_max3_f32 v147, v146, v148, v149
	v_max_f32_e32 v148, 0xefa18f08, v147
	v_sub_f32_e32 v106, v106, v148
	v_exp_f32_e32 v153, v106
	v_max3_f32 v106, v92, s92, v93
	v_max3_f32 v106, v106, v94, v95
	v_max3_f32 v106, v106, v96, v97
	v_max3_f32 v106, v106, v98, v99
	v_max3_f32 v106, v106, v100, v101
	v_max3_f32 v106, v106, v102, v103
	v_max3_f32 v106, v106, v108, v109
	v_sub_f32_e32 v104, v104, v148
	v_max3_f32 v106, v106, v110, v111
	v_exp_f32_e32 v149, v104
	v_sub_f32_e32 v104, v112, v148
	ds_bpermute_b32 v112, v201, v106
	v_exp_f32_e32 v177, v104
	v_sub_f32_e32 v104, v113, v148
	v_exp_f32_e32 v179, v104
	v_sub_f32_e32 v104, v114, v148
	s_waitcnt lgkmcnt(0)
	v_max_f32_e32 v112, v112, v112
	v_exp_f32_e32 v181, v104
	v_sub_f32_e32 v104, v115, v148
	v_max_f32_e32 v106, v106, v112
	v_sub_f32_e32 v105, v105, v148
	v_exp_f32_e32 v183, v104
	v_sub_f32_e32 v104, v116, v148
	ds_bpermute_b32 v112, v202, v106
	v_sub_f32_e32 v107, v107, v148
	v_exp_f32_e32 v151, v105
	v_exp_f32_e32 v105, v104
	v_sub_f32_e32 v104, v117, v148
	v_exp_f32_e32 v155, v107
	v_exp_f32_e32 v107, v104
	v_sub_f32_e32 v104, v118, v148
	v_exp_f32_e32 v113, v104
	v_sub_f32_e32 v104, v119, v148
	v_sub_f32_e32 v146, v146, v147
	v_exp_f32_e32 v115, v104
	v_sub_f32_e32 v104, v120, v148
	v_exp_f32_e32 v117, v104
	v_sub_f32_e32 v104, v121, v148
	v_exp_f32_e32 v185, v146
	s_waitcnt lgkmcnt(0)
; #define LAS __attribute__((address_space(3)))
; __device__ __forceinline__ unsigned pk2(float lo, float hi) { f32x2 v = {lo, hi}; bf16x2_t b = __builtin_convertvector(v, bf16x2_t); return __builtin_bit_cast(unsigned, b); }
; #define MFMA16(a, b, c) __builtin_amdgcn_mfma_f32_16x16x32_bf16(a, b, c, 0, 0, 0)
; template <int MODE> ...
;     ...
;     for (int qs = 0; qs < 2; ++qs) {
;         float mx = -1e30f;
; #pragma unroll
;         for (int s = 0; s < 4; ++s)
; #pragma unroll
;             for (int i = 0; i < 4; ++i) mx = fmaxf(mx, sc[s][qs][i]);
;         mx = fmaxf(mx, __shfl_xor(mx, 16)); mx = fmaxf(mx, __shfl_xor(mx, 32));
;         const float mn = fmaxf(mrun[qs], mx);
;         const float alpha = __builtin_amdgcn_exp2f(mrun[qs] - mn);
;         mrun[qs] = mn;
;         const float mnx = fmaxf(mn, -1e29f);
;         float ps = 0.f;
; #pragma unroll
;         for (int s = 0; s < 4; ++s)
; #pragma unroll
;             for (int i = 0; i < 4; ++i) { const float p = __builtin_amdgcn_exp2f(sc[s][qs][i] - mnx); sc[s][qs][i] = p; ps += p; }
;         lrun[qs] = lrun[qs] * alpha + ps;
; #pragma unroll
;         for (int d = 0; d < 4; ++d) O[d][qs] = O[d][qs] * alpha;
;     }
;     __builtin_amdgcn_s_setprio(1);
; #pragma unroll
;     for (int kk = 0; kk < 2; ++kk) {
;         bf16x8 Pf[2];
; #pragma unroll
;         for (int qs = 0; qs < 2; ++qs) { u32x4 w; w.x = pk2(sc[2 * kk][qs][0], sc[2 * kk][qs][1]); w.y = pk2(sc[2 * kk][qs][2], sc[2 * kk][qs][3]);
;             w.z = pk2(sc[2 * kk + 1][qs][0], sc[2 * kk + 1][qs][1]); w.w = pk2(sc[2 * kk + 1][qs][2], sc[2 * kk + 1][qs][3]); Pf[qs] = __builtin_bit_cast(bf16x8, w); }
; #pragma unroll
;         for (int d = 0; d < 4; ++d) {
;             const LAS unsigned char* vp = VT + (d * 16) * 144 + (kk * 32) * 2;
;             const s16x4 lo = *(const LAS s16x4*)vp, hi = *(const LAS s16x4*)(vp + 32);
;             const bf16x8 Vf = {lo[0], lo[1], lo[2], lo[3], hi[0], hi[1], hi[2], hi[3]};
; #pragma unroll
;             for (int qs = 0; qs < 2; ++qs) O[d][qs] = MFMA16(Vf, Pf[qs], O[d][qs]);
;             __builtin_amdgcn_sched_barrier(0);
;         }
;     }
	v_max3_f32 v146, v145, v106, v112
	v_exp_f32_e32 v119, v104
	v_sub_f32_e32 v104, v122, v148
	v_max_f32_e32 v122, 0xefa18f08, v146
	v_sub_f32_e32 v92, v92, v122
	v_exp_f32_e32 v121, v104
	v_sub_f32_e32 v104, v123, v148
	v_exp_f32_e32 v148, v92
	v_sub_f32_e32 v92, v93, v122
	v_exp_f32_e32 v150, v92
	v_sub_f32_e32 v92, v94, v122
	v_exp_f32_e32 v152, v92
	v_sub_f32_e32 v92, v95, v122
	v_exp_f32_e32 v154, v92
	v_sub_f32_e32 v92, v96, v122
	v_exp_f32_e32 v176, v92
	v_sub_f32_e32 v92, v97, v122
	v_exp_f32_e32 v178, v92
	v_pk_add_f32 v[92:93], v[148:149], 0 op_sel_hi:[1,0]
	v_sub_f32_e32 v94, v98, v122
	v_pk_add_f32 v[92:93], v[150:151], v[92:93]
	v_exp_f32_e32 v180, v94
	v_pk_add_f32 v[92:93], v[152:153], v[92:93]
	v_sub_f32_e32 v94, v99, v122
	v_pk_add_f32 v[92:93], v[154:155], v[92:93]
	v_exp_f32_e32 v182, v94
	v_sub_f32_e32 v94, v100, v122
	v_exp_f32_e32 v123, v104
	v_pk_add_f32 v[92:93], v[176:177], v[92:93]
	v_exp_f32_e32 v104, v94
	v_sub_f32_e32 v94, v101, v122
	v_pk_add_f32 v[92:93], v[178:179], v[92:93]
	v_exp_f32_e32 v106, v94
	v_sub_f32_e32 v94, v102, v122
	v_exp_f32_e32 v112, v94
	v_sub_f32_e32 v94, v103, v122
	v_pk_add_f32 v[92:93], v[180:181], v[92:93]
	v_exp_f32_e32 v114, v94
	v_sub_f32_e32 v94, v108, v122
	v_pk_add_f32 v[92:93], v[182:183], v[92:93]
	v_exp_f32_e32 v116, v94
	v_sub_f32_e32 v94, v109, v122
	v_pk_add_f32 v[92:93], v[104:105], v[92:93]
	v_exp_f32_e32 v118, v94
	v_sub_f32_e32 v94, v110, v122
	v_pk_add_f32 v[92:93], v[106:107], v[92:93]
	v_exp_f32_e32 v120, v94
	v_sub_f32_e32 v94, v111, v122
	v_pk_add_f32 v[92:93], v[112:113], v[92:93]
	v_sub_f32_e32 v145, v145, v146
	v_exp_f32_e32 v122, v94
	v_pk_add_f32 v[92:93], v[114:115], v[92:93]
	v_exp_f32_e32 v184, v145
	v_pk_add_f32 v[92:93], v[116:117], v[92:93]
	v_mov_b32_e32 v94, v185
	v_pk_add_f32 v[92:93], v[118:119], v[92:93]
	v_pk_mul_f32 v[78:79], v[78:79], v[94:95] op_sel_hi:[1,0]
	v_pk_add_f32 v[92:93], v[120:121], v[92:93]
	v_pk_mul_f32 v[76:77], v[76:77], v[94:95] op_sel_hi:[1,0]
	v_pk_add_f32 v[92:93], v[122:123], v[92:93]
	v_pk_mul_f32 v[82:83], v[82:83], v[94:95] op_sel_hi:[1,0]
	v_pk_mul_f32 v[80:81], v[80:81], v[94:95] op_sel_hi:[1,0]
	v_pk_mul_f32 v[74:75], v[74:75], v[94:95] op_sel_hi:[1,0]
	v_pk_mul_f32 v[72:73], v[72:73], v[94:95] op_sel_hi:[1,0]
	v_pk_mul_f32 v[70:71], v[70:71], v[94:95] op_sel_hi:[1,0]
	v_pk_mul_f32 v[68:69], v[68:69], v[94:95] op_sel_hi:[1,0]
	v_fma_f32 v134, v134, v184, v92
	v_fma_f32 v135, v135, v185, v93
	v_pk_mul_f32 v[66:67], v[66:67], v[184:185] op_sel_hi:[1,0]
	v_pk_mul_f32 v[64:65], v[64:65], v[184:185] op_sel_hi:[1,0]
	v_pk_mul_f32 v[62:63], v[62:63], v[184:185] op_sel_hi:[1,0]
	v_pk_mul_f32 v[60:61], v[60:61], v[184:185] op_sel_hi:[1,0]
	v_pk_mul_f32 v[58:59], v[58:59], v[184:185] op_sel_hi:[1,0]
	v_pk_mul_f32 v[56:57], v[56:57], v[184:185] op_sel_hi:[1,0]
	v_pk_mul_f32 v[54:55], v[54:55], v[184:185] op_sel_hi:[1,0]
	v_pk_mul_f32 v[52:53], v[52:53], v[184:185] op_sel_hi:[1,0]
	s_nop 0
	ds_read2_b64 v[100:103], v161 offset1:4
	v_cvt_pk_bf16_f32 v92, v149, v151
	v_cvt_pk_bf16_f32 v93, v153, v155
	v_cvt_pk_bf16_f32 v94, v177, v179
	v_cvt_pk_bf16_f32 v95, v181, v183
	v_cvt_pk_bf16_f32 v96, v148, v150
	v_cvt_pk_bf16_f32 v97, v152, v154
	v_cvt_pk_bf16_f32 v98, v176, v178
	v_cvt_pk_bf16_f32 v99, v180, v182
	s_waitcnt lgkmcnt(0)
	v_mfma_f32_16x16x32_bf16 v[76:79], v[100:103], v[92:95], v[76:79]
	v_mfma_f32_16x16x32_bf16 v[64:67], v[100:103], v[96:99], v[64:67]
	v_add_u32_e32 v108, 0x800, v161
	ds_read2_b64 v[100:103], v108 offset0:32 offset1:36
	s_waitcnt lgkmcnt(0)
	v_mfma_f32_16x16x32_bf16 v[80:83], v[100:103], v[92:95], v[80:83]
	v_mfma_f32_16x16x32_bf16 v[60:63], v[100:103], v[96:99], v[60:63]
	v_add_u32_e32 v109, 0x1000, v161
	ds_read2_b64 v[100:103], v109 offset0:64 offset1:68
	s_waitcnt lgkmcnt(0)
	v_mfma_f32_16x16x32_bf16 v[72:75], v[100:103], v[92:95], v[72:75]
	v_mfma_f32_16x16x32_bf16 v[56:59], v[100:103], v[96:99], v[56:59]
	v_add_u32_e32 v110, 0x1800, v161
	ds_read2_b64 v[100:103], v110 offset0:96 offset1:100
	s_waitcnt lgkmcnt(0)
	v_mfma_f32_16x16x32_bf16 v[68:71], v[100:103], v[92:95], v[68:71]
	v_mfma_f32_16x16x32_bf16 v[52:55], v[100:103], v[96:99], v[52:55]
	ds_read2_b64 v[100:103], v161 offset0:8 offset1:12
	v_cvt_pk_bf16_f32 v92, v105, v107
	v_cvt_pk_bf16_f32 v93, v113, v115
	v_cvt_pk_bf16_f32 v94, v117, v119
	v_cvt_pk_bf16_f32 v95, v121, v123
	v_cvt_pk_bf16_f32 v96, v104, v106
	v_cvt_pk_bf16_f32 v97, v112, v114
	v_cvt_pk_bf16_f32 v98, v116, v118
	v_cvt_pk_bf16_f32 v99, v120, v122
	s_waitcnt lgkmcnt(0)
	v_mfma_f32_16x16x32_bf16 v[76:79], v[100:103], v[92:95], v[76:79]
	v_mfma_f32_16x16x32_bf16 v[64:67], v[100:103], v[96:99], v[64:67]
	ds_read2_b64 v[100:103], v108 offset0:40 offset1:44
	s_waitcnt lgkmcnt(0)
	v_mfma_f32_16x16x32_bf16 v[80:83], v[100:103], v[92:95], v[80:83]
	v_mfma_f32_16x16x32_bf16 v[60:63], v[100:103], v[96:99], v[60:63]
	ds_read2_b64 v[100:103], v109 offset0:72 offset1:76
	s_waitcnt lgkmcnt(0)
	v_mfma_f32_16x16x32_bf16 v[72:75], v[100:103], v[92:95], v[72:75]
	v_mfma_f32_16x16x32_bf16 v[56:59], v[100:103], v[96:99], v[56:59]
	ds_read2_b64 v[100:103], v110 offset0:104 offset1:108
	s_waitcnt lgkmcnt(0)
	v_mfma_f32_16x16x32_bf16 v[68:71], v[100:103], v[92:95], v[68:71]
	v_mfma_f32_16x16x32_bf16 v[52:55], v[100:103], v[96:99], v[52:55]
	s_nop 0
	s_cmp_lt_i32 s8, 0
	s_cbranch_scc1 .LBB0_1113
	s_mov_b32 s9, s8
	s_mov_b64 s[6:7], s[0:1]
	v_mov_b32_e32 v145, v146
	v_mov_b32_e32 v146, v147
	s_branch .LBB0_1101

; __device__ __forceinline__ unsigned pk2(float lo, float hi) { f32x2 v = {lo, hi}; bf16x2_t b = __builtin_convertvector(v, bf16x2_t); return __builtin_bit_cast(unsigned, b); }
; template <int MODE> ...
;     ...
;     for (int qs = 0; qs < 2; ++qs) {
;         float mx = -1e30f;
; #pragma unroll
;         for (int s = 0; s < 4; ++s)
; #pragma unroll
;             for (int i = 0; i < 4; ++i) mx = fmaxf(mx, sc[s][qs][i]);
;         mx = fmaxf(mx, __shfl_xor(mx, 16)); mx = fmaxf(mx, __shfl_xor(mx, 32));
;         const float mn = fmaxf(mrun[qs], mx);
;         const float alpha = __builtin_amdgcn_exp2f(mrun[qs] - mn);
;         mrun[qs] = mn;
;         const float mnx = fmaxf(mn, -1e29f);
;         float ps = 0.f;
; #pragma unroll
;         for (int s = 0; s < 4; ++s)
; #pragma unroll
;             for (int i = 0; i < 4; ++i) { const float p = __builtin_amdgcn_exp2f(sc[s][qs][i] - mnx); sc[s][qs][i] = p; ps += p; }
;         lrun[qs] = lrun[qs] * alpha + ps;
; #pragma unroll
;         for (int d = 0; d < 4; ++d) O[d][qs] = O[d][qs] * alpha;
;     }
;     __builtin_amdgcn_s_setprio(1);
; #pragma unroll
;     for (int kk = 0; kk < 2; ++kk) {
;         bf16x8 Pf[2];
; #pragma unroll
;         for (int qs = 0; qs < 2; ++qs) { u32x4 w; w.x = pk2(sc[2 * kk][qs][0], sc[2 * kk][qs][1]); w.y = pk2(sc[2 * kk][qs][2], sc[2 * kk][qs][3]);
;             w.z = pk2(sc[2 * kk + 1][qs][0], sc[2 * kk + 1][qs][1]); w.w = pk2(sc[2 * kk + 1][qs][2], sc[2 * kk + 1][qs][3]); Pf[qs] = __builtin_bit_cast(bf16x8, w); }
.LBB0_1115:
	v_max3_f32 v161, v136, s92, v137
	v_max3_f32 v161, v161, v138, v139
	v_max3_f32 v161, v161, v144, v145
	v_max3_f32 v161, v161, v146, v147
	v_max3_f32 v161, v161, v148, v149
	v_max3_f32 v161, v161, v150, v151
	v_max3_f32 v161, v161, v152, v153
	v_max3_f32 v161, v161, v154, v155
	ds_bpermute_b32 v210, v201, v161
	v_add_u32_e32 v226, 0, v209
	s_waitcnt lgkmcnt(0)
	v_max_f32_e32 v210, v210, v210
	v_max_f32_e32 v161, v161, v210
	ds_bpermute_b32 v210, v202, v161
	s_waitcnt lgkmcnt(0)
	v_max3_f32 v161, v208, v161, v210
	v_max_f32_e32 v210, 0xefa18f08, v161
	v_sub_f32_e32 v138, v138, v210
	v_exp_f32_e32 v213, v138
	v_max3_f32 v138, v124, s92, v125
	v_max3_f32 v138, v138, v126, v127
	v_max3_f32 v138, v138, v128, v129
	v_max3_f32 v138, v138, v130, v131
	v_max3_f32 v138, v138, v132, v133
	v_max3_f32 v138, v138, v134, v135
	v_max3_f32 v138, v138, v140, v141
	v_sub_f32_e32 v136, v136, v210
	v_max3_f32 v138, v138, v142, v143
	v_exp_f32_e32 v209, v136
	v_sub_f32_e32 v136, v144, v210
	ds_bpermute_b32 v144, v201, v138
	v_exp_f32_e32 v217, v136
	v_sub_f32_e32 v136, v145, v210
	v_exp_f32_e32 v219, v136
	v_sub_f32_e32 v136, v146, v210
	s_waitcnt lgkmcnt(0)
	v_max_f32_e32 v144, v144, v144
	v_exp_f32_e32 v221, v136
	v_sub_f32_e32 v136, v147, v210
	v_max_f32_e32 v138, v138, v144
	v_sub_f32_e32 v137, v137, v210
	v_exp_f32_e32 v223, v136
	v_sub_f32_e32 v136, v148, v210
	ds_bpermute_b32 v144, v202, v138
	v_sub_f32_e32 v139, v139, v210
	v_exp_f32_e32 v211, v137
	v_exp_f32_e32 v137, v136
	v_sub_f32_e32 v136, v149, v210
	v_exp_f32_e32 v215, v139
	v_exp_f32_e32 v139, v136
	v_sub_f32_e32 v136, v150, v210
	v_exp_f32_e32 v145, v136
	v_sub_f32_e32 v136, v151, v210
	v_exp_f32_e32 v147, v136
	v_sub_f32_e32 v136, v152, v210
	v_exp_f32_e32 v149, v136
	v_sub_f32_e32 v136, v153, v210
	s_waitcnt lgkmcnt(0)
	v_max3_f32 v227, v207, v138, v144
	v_exp_f32_e32 v151, v136
	v_sub_f32_e32 v136, v154, v210
	v_max_f32_e32 v154, 0xefa18f08, v227
	v_sub_f32_e32 v208, v208, v161
	v_sub_f32_e32 v124, v124, v154
	v_exp_f32_e32 v225, v208
	v_exp_f32_e32 v208, v124
	v_sub_f32_e32 v124, v125, v154
	v_exp_f32_e32 v153, v136
	v_sub_f32_e32 v136, v155, v210
	v_exp_f32_e32 v210, v124
	v_sub_f32_e32 v124, v126, v154
	v_exp_f32_e32 v212, v124
	v_sub_f32_e32 v124, v127, v154
	v_exp_f32_e32 v214, v124
	v_sub_f32_e32 v124, v128, v154
	v_exp_f32_e32 v216, v124
	v_sub_f32_e32 v124, v129, v154
	v_exp_f32_e32 v218, v124
	v_sub_f32_e32 v124, v130, v154
	v_exp_f32_e32 v220, v124
	v_sub_f32_e32 v124, v131, v154
	v_exp_f32_e32 v222, v124
	v_pk_add_f32 v[124:125], v[208:209], 0 op_sel_hi:[1,0]
	v_sub_f32_e32 v126, v132, v154
	v_pk_add_f32 v[124:125], v[210:211], v[124:125]
	v_exp_f32_e32 v155, v136
	v_pk_add_f32 v[124:125], v[212:213], v[124:125]
	v_exp_f32_e32 v136, v126
	v_pk_add_f32 v[124:125], v[214:215], v[124:125]
	v_sub_f32_e32 v126, v133, v154
	v_pk_add_f32 v[124:125], v[216:217], v[124:125]
	v_exp_f32_e32 v138, v126
	v_pk_add_f32 v[124:125], v[218:219], v[124:125]
	v_sub_f32_e32 v126, v134, v154
	v_pk_add_f32 v[124:125], v[220:221], v[124:125]
	v_exp_f32_e32 v144, v126
	v_sub_f32_e32 v126, v135, v154
	v_pk_add_f32 v[124:125], v[222:223], v[124:125]
	v_exp_f32_e32 v146, v126
	v_sub_f32_e32 v126, v140, v154
	v_exp_f32_e32 v148, v126
	v_sub_f32_e32 v126, v141, v154
	v_pk_add_f32 v[124:125], v[136:137], v[124:125]
	v_exp_f32_e32 v150, v126
	v_sub_f32_e32 v126, v142, v154
	v_pk_add_f32 v[124:125], v[138:139], v[124:125]
	v_exp_f32_e32 v152, v126
	v_sub_f32_e32 v126, v143, v154
	v_pk_add_f32 v[124:125], v[144:145], v[124:125]
	v_sub_f32_e32 v207, v207, v227
	v_exp_f32_e32 v154, v126
	v_pk_add_f32 v[124:125], v[146:147], v[124:125]
	v_exp_f32_e32 v224, v207
	v_pk_add_f32 v[124:125], v[148:149], v[124:125]
	v_mov_b32_e32 v126, v225
	v_pk_add_f32 v[124:125], v[150:151], v[124:125]
	v_pk_mul_f32 v[118:119], v[118:119], v[126:127] op_sel_hi:[1,0]
	v_pk_add_f32 v[124:125], v[152:153], v[124:125]
	v_pk_mul_f32 v[116:117], v[116:117], v[126:127] op_sel_hi:[1,0]
	v_pk_add_f32 v[124:125], v[154:155], v[124:125]
	v_pk_mul_f32 v[122:123], v[122:123], v[126:127] op_sel_hi:[1,0]
	v_pk_mul_f32 v[120:121], v[120:121], v[126:127] op_sel_hi:[1,0]
	v_pk_mul_f32 v[114:115], v[114:115], v[126:127] op_sel_hi:[1,0]
	v_pk_mul_f32 v[112:113], v[112:113], v[126:127] op_sel_hi:[1,0]
	v_pk_mul_f32 v[110:111], v[110:111], v[126:127] op_sel_hi:[1,0]
	v_pk_mul_f32 v[108:109], v[108:109], v[126:127] op_sel_hi:[1,0]
	v_fma_f32 v176, v176, v224, v124
	v_fma_f32 v177, v177, v225, v125
	v_pk_mul_f32 v[106:107], v[106:107], v[224:225] op_sel_hi:[1,0]
	v_pk_mul_f32 v[104:105], v[104:105], v[224:225] op_sel_hi:[1,0]
	v_pk_mul_f32 v[102:103], v[102:103], v[224:225] op_sel_hi:[1,0]
	v_pk_mul_f32 v[100:101], v[100:101], v[224:225] op_sel_hi:[1,0]
	v_pk_mul_f32 v[98:99], v[98:99], v[224:225] op_sel_hi:[1,0]
	v_pk_mul_f32 v[96:97], v[96:97], v[224:225] op_sel_hi:[1,0]
	v_pk_mul_f32 v[94:95], v[94:95], v[224:225] op_sel_hi:[1,0]
	v_pk_mul_f32 v[92:93], v[92:93], v[224:225] op_sel_hi:[1,0]
	s_nop 0
	ds_read2_b64 v[132:135], v226 offset1:4
	v_cvt_pk_bf16_f32 v124, v209, v211
	v_cvt_pk_bf16_f32 v125, v213, v215
	v_cvt_pk_bf16_f32 v126, v217, v219
	v_cvt_pk_bf16_f32 v127, v221, v223
	v_cvt_pk_bf16_f32 v128, v208, v210
	v_cvt_pk_bf16_f32 v129, v212, v214
	v_cvt_pk_bf16_f32 v130, v216, v218
	v_cvt_pk_bf16_f32 v131, v220, v222
	s_waitcnt lgkmcnt(0)
; #define LAS __attribute__((address_space(3)))
; __device__ __forceinline__ unsigned pk2(float lo, float hi) { f32x2 v = {lo, hi}; bf16x2_t b = __builtin_convertvector(v, bf16x2_t); return __builtin_bit_cast(unsigned, b); }
; #define MFMA16(a, b, c) __builtin_amdgcn_mfma_f32_16x16x32_bf16(a, b, c, 0, 0, 0)
; template <int MODE> ...
;     ...
;     __builtin_amdgcn_s_setprio(1);
; #pragma unroll
;     for (int kk = 0; kk < 2; ++kk) {
;         bf16x8 Pf[2];
; #pragma unroll
;         for (int qs = 0; qs < 2; ++qs) { u32x4 w; w.x = pk2(sc[2 * kk][qs][0], sc[2 * kk][qs][1]); w.y = pk2(sc[2 * kk][qs][2], sc[2 * kk][qs][3]);
;             w.z = pk2(sc[2 * kk + 1][qs][0], sc[2 * kk + 1][qs][1]); w.w = pk2(sc[2 * kk + 1][qs][2], sc[2 * kk + 1][qs][3]); Pf[qs] = __builtin_bit_cast(bf16x8, w); }
; #pragma unroll
;         for (int d = 0; d < 4; ++d) {
;             const LAS unsigned char* vp = VT + (d * 16) * 144 + (kk * 32) * 2;
;             const s16x4 lo = *(const LAS s16x4*)vp, hi = *(const LAS s16x4*)(vp + 32);
;             const bf16x8 Vf = {lo[0], lo[1], lo[2], lo[3], hi[0], hi[1], hi[2], hi[3]};
; #pragma unroll
;             for (int qs = 0; qs < 2; ++qs) O[d][qs] = MFMA16(Vf, Pf[qs], O[d][qs]);
;             __builtin_amdgcn_sched_barrier(0);
;         }
;     }
; __device__ __forceinline__ void nsa_phase(LAS unsigned char* lds, const Args& a, const bf16_t* z, const bf16_t* KC, const bf16_t* VCT, const bf16_t* VST, const bf16_t* VWT, bf16_t* A2, int ldo, bool merged) {
;     ...
;             for (; j <= cur; ++j) {
;                 __syncthreads();
;                 nsa_commit(lds, pkv, pvv, tidv);
;                 __syncthreads();
;                 if (j < cur) nsa_fetch(pkv, pvv, z + ((size_t)b * SEQ + (j + 1) * 64) * ZLD + ZKW + g * 64, ZLD, VWT + ((size_t)(b * 128 + g * 64)) * SEQ + (j + 1) * 64, SEQ, tidv);
;                 flash_tile<2>(lds, kt_off, vt_off, Qf, O, mrun, lrun, slope, tq, j * 64, selb, l15, g4, (j < cur) && (j > cur - 8));
	v_mfma_f32_16x16x32_bf16 v[116:119], v[132:135], v[124:127], v[116:119]
	v_mfma_f32_16x16x32_bf16 v[104:107], v[132:135], v[128:131], v[104:107]
	v_add_u32_e32 v140, 0x800, v226
	ds_read2_b64 v[132:135], v140 offset0:32 offset1:36
	s_waitcnt lgkmcnt(0)
	v_mfma_f32_16x16x32_bf16 v[120:123], v[132:135], v[124:127], v[120:123]
	v_mfma_f32_16x16x32_bf16 v[100:103], v[132:135], v[128:131], v[100:103]
	v_add_u32_e32 v141, 0x1000, v226
	ds_read2_b64 v[132:135], v141 offset0:64 offset1:68
	s_waitcnt lgkmcnt(0)
	v_mfma_f32_16x16x32_bf16 v[112:115], v[132:135], v[124:127], v[112:115]
	v_mfma_f32_16x16x32_bf16 v[96:99], v[132:135], v[128:131], v[96:99]
	v_add_u32_e32 v142, 0x1800, v226
	ds_read2_b64 v[132:135], v142 offset0:96 offset1:100
	s_waitcnt lgkmcnt(0)
	v_mfma_f32_16x16x32_bf16 v[108:111], v[132:135], v[124:127], v[108:111]
	v_mfma_f32_16x16x32_bf16 v[92:95], v[132:135], v[128:131], v[92:95]
	ds_read2_b64 v[132:135], v226 offset0:8 offset1:12
	v_cvt_pk_bf16_f32 v124, v137, v139
	v_cvt_pk_bf16_f32 v125, v145, v147
	v_cvt_pk_bf16_f32 v126, v149, v151
	v_cvt_pk_bf16_f32 v127, v153, v155
	v_cvt_pk_bf16_f32 v128, v136, v138
	v_cvt_pk_bf16_f32 v129, v144, v146
	v_cvt_pk_bf16_f32 v130, v148, v150
	v_cvt_pk_bf16_f32 v131, v152, v154
	s_waitcnt lgkmcnt(0)
	v_mfma_f32_16x16x32_bf16 v[116:119], v[132:135], v[124:127], v[116:119]
	v_mfma_f32_16x16x32_bf16 v[104:107], v[132:135], v[128:131], v[104:107]
	ds_read2_b64 v[132:135], v140 offset0:40 offset1:44
	s_waitcnt lgkmcnt(0)
	v_mfma_f32_16x16x32_bf16 v[120:123], v[132:135], v[124:127], v[120:123]
	v_mfma_f32_16x16x32_bf16 v[100:103], v[132:135], v[128:131], v[100:103]
	ds_read2_b64 v[132:135], v141 offset0:72 offset1:76
	s_waitcnt lgkmcnt(0)
	v_mfma_f32_16x16x32_bf16 v[112:115], v[132:135], v[124:127], v[112:115]
	v_mfma_f32_16x16x32_bf16 v[96:99], v[132:135], v[128:131], v[96:99]
	ds_read2_b64 v[132:135], v142 offset0:104 offset1:108
	s_waitcnt lgkmcnt(0)
	v_mfma_f32_16x16x32_bf16 v[108:111], v[132:135], v[124:127], v[108:111]
	v_mfma_f32_16x16x32_bf16 v[92:95], v[132:135], v[128:131], v[92:95]
	s_nop 0
	s_add_i32 s77, s77, 1
	s_add_i32 s79, s79, 64
	v_subrev_u32_e32 v3, 64, v3
	s_and_b64 vcc, exec, s[74:75]
	v_mov_b32_e32 v208, v161
	v_mov_b32_e32 v207, v227
	s_cbranch_vccnz .LBB0_912

; #define LAS __attribute__((address_space(3)))
; #define MFMA16(a, b, c) __builtin_amdgcn_mfma_f32_16x16x32_bf16(a, b, c, 0, 0, 0)
; template <int MODE> ...
;     asm volatile("" : "+v"(kt_off), "+v"(vt_off));
;     const LAS unsigned char* KT = lds + kt_off; const LAS unsigned char* VT = lds + vt_off;
;     f32x4 sc[4][2];
;     float cb[2];
; #pragma unroll
;     for (int qs = 0; qs < 2; ++qs) cb[qs] = slope * (float)(key0 + 4 * g4 - tq[qs]) + ((MODE == 1 && !selb[qs]) ? -1e30f : 0.f);
;     __builtin_amdgcn_s_setprio(1);
; #pragma unroll
;     for (int s = 0; s < 4; ++s) {
;         const LAS unsigned char* kp = KT + (s * 16) * 144;
;         const bf16x8 k0 = *(const LAS bf16x8*)kp, k1 = *(const LAS bf16x8*)(kp + 64);
; #pragma unroll
;         for (int qs = 0; qs < 2; ++qs) {
;             f32x4 zz;
; #pragma unroll
;             for (int i = 0; i < 4; ++i) zz[i] = fmaf(slope, (float)(s * 16 + i), cb[qs]);
;             zz = MFMA16(k0, Qf[qs][0], zz);
;             sc[s][qs] = MFMA16(k1, Qf[qs][1], zz);
;         }
;         __builtin_amdgcn_sched_barrier(0);
;     }
;     __builtin_amdgcn_s_setprio(0);
;     if (!full) {
; #pragma unroll
;         for (int qs = 0; qs < 2; ++qs)
; #pragma unroll
;             for (int s = 0; s < 4; ++s)
; #pragma unroll
;                 for (int i = 0; i < 4; ++i) {
;                     const int dist = (tq[qs] - key0 - 4 * g4) - (s * 16 + i);
;                     const bool ok = (MODE == 1) ? (dist >= 0) : (dist >= 0 && dist < 512);
;                     sc[s][qs][i] = ok ? sc[s][qs][i] : -1e30f;
;                 }
.LBB0_1118:
	v_add_u32_e32 v125, s79, v204
	v_cvt_f32_i32_e32 v126, v125
	v_add_u32_e32 v125, -16, v125
	v_cvt_f32_i32_e32 v125, v125
	s_cmp_gt_i32 s77, s69
	s_cselect_b64 s[6:7], -1, 0
	v_mov_b32_e32 v124, v1
	v_mov_b32_e32 v209, v203
	s_and_b64 s[0:1], s[0:1], s[6:7]
	v_fma_f32 v210, v160, v126, 0
	v_add_u32_e32 v215, 0, v124
	v_fma_f32 v214, v160, v125, 0
	s_nop 0
	ds_read_b128 v[124:127], v215
	v_fma_f32 v128, 0, v160, v210
	v_add_f32_e32 v129, v160, v210
	v_fma_f32 v130, v162, s56, v210
	v_fma_f32 v131, v163, s57, v210
	v_fma_f32 v132, 0, v160, v214
	v_add_f32_e32 v133, v160, v214
	v_fma_f32 v134, v162, s56, v214
	v_fma_f32 v135, v163, s57, v214
	s_waitcnt lgkmcnt(0)
	v_mfma_f32_16x16x32_bf16 v[128:131], v[124:127], v[4:7], v[128:131]
	v_mfma_f32_16x16x32_bf16 v[124:127], v[124:127], v[12:15], v[132:135]
	s_nop 2
	ds_read_b128 v[132:135], v215 offset:64
	s_waitcnt lgkmcnt(0)
	v_mfma_f32_16x16x32_bf16 v[136:139], v[132:135], v[8:11], v[128:131]
	v_mfma_f32_16x16x32_bf16 v[124:127], v[132:135], v[16:19], v[124:127]
	s_nop 1
	ds_read_b128 v[128:131], v215 offset:2304
	v_mov_b32_e32 v161, v160
	v_fma_f32 v132, v164, s88, v210
	v_fma_f32 v133, v165, s89, v210
	v_fma_f32 v134, v160, s20, v210
	v_fma_f32 v135, v161, s21, v210
	v_fma_f32 v140, v164, s88, v214
	v_fma_f32 v141, v165, s89, v214
	v_fma_f32 v142, v160, s20, v214
	v_fma_f32 v143, v161, s21, v214
	s_waitcnt lgkmcnt(0)
	v_mfma_f32_16x16x32_bf16 v[132:135], v[128:131], v[4:7], v[132:135]
	v_mfma_f32_16x16x32_bf16 v[128:131], v[128:131], v[12:15], v[140:143]
	s_nop 2
	ds_read_b128 v[140:143], v215 offset:2368
	s_waitcnt lgkmcnt(0)
	v_mfma_f32_16x16x32_bf16 v[144:147], v[140:143], v[8:11], v[132:135]
	v_mfma_f32_16x16x32_bf16 v[128:131], v[140:143], v[16:19], v[128:131]
	s_nop 1
	ds_read_b128 v[132:135], v215 offset:4608
	ds_read_b128 v[152:155], v215 offset:4672
	v_fma_f32 v142, v160, s54, v210
	v_fma_f32 v143, v161, s55, v210
	v_fma_f32 v140, v164, s80, v210
	v_fma_f32 v141, v165, s81, v210
	v_fma_f32 v150, v160, s54, v214
	v_fma_f32 v151, v161, s55, v214
	v_fma_f32 v148, v164, s80, v214
	v_fma_f32 v149, v165, s81, v214
	s_waitcnt lgkmcnt(1)
	v_mfma_f32_16x16x32_bf16 v[140:143], v[132:135], v[4:7], v[140:143]
	v_mfma_f32_16x16x32_bf16 v[132:135], v[132:135], v[12:15], v[148:151]
	s_waitcnt lgkmcnt(0)
	v_mfma_f32_16x16x32_bf16 v[148:151], v[152:155], v[8:11], v[140:143]
	v_mfma_f32_16x16x32_bf16 v[132:135], v[152:155], v[16:19], v[132:135]
	s_nop 3
	ds_read_b128 v[140:143], v215 offset:6912
	v_fma_f32 v154, v160, s44, v210
	v_fma_f32 v155, v161, s45, v210
	v_fma_f32 v152, v164, s40, v210
	v_fma_f32 v153, v165, s41, v210
	v_fma_f32 v212, v160, s44, v214
	v_fma_f32 v213, v161, s45, v214
	v_fma_f32 v210, v164, s40, v214
	v_fma_f32 v211, v165, s41, v214
	s_waitcnt lgkmcnt(0)
	v_mfma_f32_16x16x32_bf16 v[152:155], v[140:143], v[4:7], v[152:155]
	v_mfma_f32_16x16x32_bf16 v[140:143], v[140:143], v[12:15], v[210:213]
	s_nop 2
	ds_read_b128 v[210:213], v215 offset:6976
	s_waitcnt lgkmcnt(0)
	v_mfma_f32_16x16x32_bf16 v[152:155], v[210:213], v[8:11], v[152:155]
	v_mfma_f32_16x16x32_bf16 v[140:143], v[210:213], v[16:19], v[140:143]
	s_nop 0
	s_and_b64 vcc, exec, s[0:1]
	s_cbranch_vccnz .LBB0_1115
	v_add_u32_e32 v161, 51, v3
	v_cmp_gt_u32_e32 vcc, s35, v161
	v_add_u32_e32 v161, 50, v3
	v_cmp_gt_u32_e64 s[0:1], s35, v161
	v_add_u32_e32 v161, 49, v3
	v_cmp_gt_u32_e64 s[6:7], s35, v161
	v_add_u32_e32 v161, 48, v3
	v_cmp_gt_u32_e64 s[8:9], s35, v161
	v_add_u32_e32 v161, 35, v3
	v_cmp_gt_u32_e64 s[10:11], s35, v161
	v_add_u32_e32 v161, 34, v3
	v_cmp_gt_u32_e64 s[12:13], s35, v161
	v_add_u32_e32 v161, 33, v3
	v_cmp_gt_u32_e64 s[14:15], s35, v161
	v_add_u32_e32 v161, 32, v3
	v_cmp_gt_u32_e64 s[16:17], s35, v161
	v_add_u32_e32 v161, 19, v3
	v_cmp_gt_u32_e64 s[18:19], s35, v161
	v_add_u32_e32 v161, 18, v3
	v_cmp_gt_u32_e64 s[22:23], s35, v161
	v_add_u32_e32 v161, 17, v3
	v_cmp_gt_u32_e64 s[24:25], s35, v161
	v_add_u32_e32 v161, 16, v3
	v_cmp_gt_u32_e64 s[26:27], s35, v161
	v_add_u32_e32 v161, 3, v3
	v_cmp_gt_u32_e64 s[28:29], s35, v161
	v_add_u32_e32 v161, 2, v3
	v_cndmask_b32_e32 v136, v194, v136, vcc
	v_cndmask_b32_e64 v152, v194, v152, s[28:29]
	v_cmp_gt_u32_e64 s[28:29], s35, v161
	v_add_u32_e32 v161, 1, v3
	v_cndmask_b32_e64 v137, v194, v137, s[0:1]
	v_cndmask_b32_e64 v153, v194, v153, s[28:29]
	v_cmp_gt_u32_e64 s[28:29], s35, v161
	v_add_u32_e32 v161, 0x43, v3
	v_cndmask_b32_e64 v138, v194, v138, s[6:7]
	v_cndmask_b32_e64 v154, v194, v154, s[28:29]
	v_cmp_gt_u32_e64 s[28:29], s35, v3
	v_cndmask_b32_e64 v139, v194, v139, s[8:9]
	v_cndmask_b32_e64 v144, v194, v144, s[10:11]
	v_cndmask_b32_e64 v155, v194, v155, s[28:29]
	v_cmp_gt_u32_e64 s[28:29], s35, v161
	v_add_u32_e32 v161, 0x42, v3
	v_cndmask_b32_e64 v145, v194, v145, s[12:13]
	v_cndmask_b32_e64 v124, v194, v124, s[28:29]
	v_cmp_gt_u32_e64 s[28:29], s35, v161
	v_add_u32_e32 v161, 0x41, v3
	v_cndmask_b32_e64 v146, v194, v146, s[14:15]
	v_cndmask_b32_e64 v125, v194, v125, s[28:29]
	v_cmp_gt_u32_e64 s[28:29], s35, v161
	v_add_u32_e32 v161, 64, v3
	v_cndmask_b32_e64 v147, v194, v147, s[16:17]
	v_cndmask_b32_e64 v126, v194, v126, s[28:29]
	v_cmp_gt_u32_e64 s[28:29], s35, v161
	v_cndmask_b32_e64 v148, v194, v148, s[18:19]
	v_cndmask_b32_e64 v149, v194, v149, s[22:23]
	v_cndmask_b32_e64 v150, v194, v150, s[24:25]
	v_cndmask_b32_e64 v151, v194, v151, s[26:27]
	v_cndmask_b32_e64 v127, v194, v127, s[28:29]
	v_cndmask_b32_e32 v128, v194, v128, vcc
	v_cndmask_b32_e64 v129, v194, v129, s[0:1]
	v_cndmask_b32_e64 v130, v194, v130, s[6:7]
	v_cndmask_b32_e64 v131, v194, v131, s[8:9]
	v_cndmask_b32_e64 v132, v194, v132, s[10:11]
	v_cndmask_b32_e64 v133, v194, v133, s[12:13]
	v_cndmask_b32_e64 v134, v194, v134, s[14:15]
	v_cndmask_b32_e64 v135, v194, v135, s[16:17]
	v_cndmask_b32_e64 v140, v194, v140, s[18:19]
	v_cndmask_b32_e64 v141, v194, v141, s[22:23]
	v_cndmask_b32_e64 v142, v194, v142, s[24:25]
	v_cndmask_b32_e64 v143, v194, v143, s[26:27]
	s_branch .LBB0_1115
